# new symmetric P1 K-loop + attention epilogue z-load hoist
# speedup vs baseline: 1.0092x; 1.0092x over previous
; #define PG8_STAGE(bufoff, gbase, voff) do { _Pragma("unroll") for (int _i = 0; _i < 2; ++_i) \
;         __builtin_amdgcn_global_load_lds((const unsigned*)((const char*)(gbase) + (voff)[_i]), (LAS unsigned*)(lds + (bufoff) + ldsw + _i * 8192), 16, 0, 0); } while (0)
; #define PG8_WAIT_V(n) asm volatile("s_waitcnt vmcnt(" #n ")" ::: "memory")
; #define PG8_BAR __builtin_amdgcn_s_barrier()
; template <class Epi, class Sched, int NSEG, bool ALIGN_EPI = true, bool AFTER_DRAIN = false>
; __device__ __forceinline__ void gemm_phase(LAS unsigned char* lds, const Gemm g, const Sched& S, const Epi& E) {
;     ...
;     const unsigned ldsw = (unsigned)wid * 1024u;
;     const int aoff = lds_byte(wr * 64 + fr, fq * 8), boff = lds_byte(wc * 32 + fr, fq * 8);
;     ...
;     PG8_STAGE(PG8_SB(0, 0), cB, voffB); PG8_STAGE(PG8_SB(0, 1), cB + hstep, voffB); PG8_STAGE(PG8_SA(0, 0), cA, voffA); PG8_STAGE(PG8_SA(0, 1), cA + hstep, voffA);
;     if (wr == 1) PG8_BAR;
;     PG8_WAIT_V(2); PG8_BAR;
;     PG8_STAGE(PG8_SB(1, 0), cB + kstep, voffB); PG8_STAGE(PG8_SA(1, 0), cA + kstep, voffA); PG8_STAGE(PG8_SB(1, 1), cB + hstep + kstep, voffB);
;     PG8_WAIT_V(6); PG8_BAR;
.LBB0_321:
	s_lshl_b32 s1, s1, 5
	s_mov_b64 s[10:11], 0x80
	s_and_b32 s1, s1, 0x60
	s_add_i32 m0, s33, 0x18000
	v_lshl_add_u64 v[6:7], v[6:7], 0, s[10:11]
	s_ashr_i32 s39, s96, 31
	s_ashr_i32 s40, s97, 31
	s_lshl_b32 s3, s0, 13
	s_lshl_b32 s13, s1, 7
	global_load_lds_dwordx4 v[6:7], off
	v_lshl_add_u64 v[4:5], v[4:5], 0, s[10:11]
	s_add_i32 m0, s33, 0x1a000
	s_add_i32 s41, s33, 0x8000
	s_add_i32 s42, s33, 0xa000
	global_load_lds_dwordx4 v[4:5], off
	v_lshl_add_u64 v[0:1], v[0:1], 0, s[10:11]
	s_mov_b32 m0, s41
	s_add_u32 s16, s28, 0x80080
	global_load_lds_dwordx4 v[0:1], off
	v_lshl_add_u64 v[0:1], v[2:3], 0, s[10:11]
	s_mov_b32 m0, s42
	s_addc_u32 s17, s29, 0
	global_load_lds_dwordx4 v[0:1], off
	s_add_i32 m0, s33, 0x1c000
	v_lshl_add_u64 v[0:1], s[16:17], 0, v[140:141]
	global_load_lds_dwordx4 v[0:1], off
	v_lshl_add_u64 v[0:1], s[16:17], 0, v[144:145]
	s_add_i32 m0, s33, 0x1e000
	s_movk_i32 s14, 0x3c0
	global_load_lds_dwordx4 v[0:1], off
	s_add_u32 s74, s26, 0x80080
	s_addc_u32 s75, s27, 0
	s_add_i32 m0, s33, 0xc000
	s_add_u32 s72, s26, 0x100
	global_load_lds_dwordx4 v138, s[74:75]
	s_add_i32 m0, s33, 0xe000
	s_addc_u32 s73, s27, 0
	global_load_lds_dwordx4 v142, s[74:75]
	s_add_u32 s76, s28, 0x100
	s_addc_u32 s77, s29, 0
	v_lshlrev_b32_e32 v0, 1, v11
	v_lshlrev_b32_e32 v1, 6, v186
	v_lshlrev_b32_e32 v2, 2, v186
	v_and_or_b32 v1, v1, s14, v0
	v_and_b32_e32 v2, 32, v2
	v_bitop3_b32 v149, s13, v1, v2 bitop3:0xf6
	v_lshlrev_b32_e32 v1, 9, v186
	v_and_b32_e32 v1, 0xffff0000, v1
	v_lshlrev_b32_e32 v2, 12, v10
	v_or3_b32 v1, v8, v1, v2
	v_lshlrev_b32_e32 v3, 2, v136
	v_add_u32_e32 v150, v1, v9
	v_lshlrev_b32_e32 v1, 5, v12
	v_lshl_or_b32 v0, v136, 6, v0
	v_and_b32_e32 v3, 32, v3
	s_waitcnt vmcnt(8)
	s_cmpk_lt_u32 s12, 0x100
	v_and_b32_e32 v1, 0xffff0000, v1
	v_lshl_or_b32 v137, s0, 6, v136
	v_bitop3_b32 v0, v0, s3, v3 bitop3:0xde
	s_cselect_b64 s[12:13], -1, 0
	v_or3_b32 v1, v8, v1, v2
	s_add_i32 s43, 0, 0x10000
	s_add_i32 s44, 0, 0x14000
	v_or_b32_e32 v148, s1, v11
	v_add_u32_e32 v160, 2, v137
	v_add_u32_e32 v161, 64, v137
	v_mov_b32_e32 v151, v147
	v_add_u32_e32 v152, v1, v9
	v_mov_b32_e32 v153, v147
	v_mov_b64_e32 v[154:155], 0xa00
	v_mov_b64_e32 v[156:157], 0x9ff
	v_add_u32_e32 v162, s43, v149
	v_add_u32_e32 v163, s44, v149
	v_add_u32_e32 v164, 0, v0
	s_mov_b32 s45, 0x20000
	s_mov_b32 s46, 0x30000
	s_mov_b32 s47, 0x80000
	s_mov_b32 s48, 0x90000
	s_mov_b32 s49, 0xa0000
	s_mov_b32 s14, 0x3e0293ee
	v_mov_b32_e32 v165, 0x1040
	s_barrier
	s_branch .LBB0_324

; #define PG8_STAGE(bufoff, gbase, voff) do { _Pragma("unroll") for (int _i = 0; _i < 2; ++_i) \
;         __builtin_amdgcn_global_load_lds((const unsigned*)((const char*)(gbase) + (voff)[_i]), (LAS unsigned*)(lds + (bufoff) + ldsw + _i * 8192), 16, 0, 0); } while (0)
; #define PG8_LDA(dst, b, h) do { _Pragma("unroll") for (int m = 0; m < 4; ++m) _Pragma("unroll") for (int k = 0; k < 2; ++k) dst[m][k] = *(const LAS bf16x8*)(lds + PG8_SA(b, h) + aoff + m * 2048 + k * 1024); } while (0)
; #define PG8_LDB(dst, b, h) do { _Pragma("unroll") for (int n = 0; n < 2; ++n) _Pragma("unroll") for (int k = 0; k < 2; ++k) dst[n][k] = *(const LAS bf16x8*)(lds + PG8_SB(b, h) + boff + n * 2048 + k * 1024); } while (0)
; #define PG8_SCHED __builtin_amdgcn_sched_barrier(0)
; template <class Epi, class Sched, int NSEG, bool ALIGN_EPI = true, bool AFTER_DRAIN = false>
; __device__ __forceinline__ void gemm_phase(LAS unsigned char* lds, const Gemm g, const Sched& S, const Epi& E) {
;     ...
;         const bool has_next = S.next(ui + 1, nxt);
;         const char* nA = has_next ? PG8_ABASE(nxt) : cA; const char* nB = has_next ? PG8_BBASE(nxt) : cB;
;         for (int t = 0; t < nt; t += 2) {
;             const bool last = (t == nt - 2);
;             const char* a1 = cA + (size_t)(t + 1) * kstep;
;             const char* a2 = last ? nA : cA + (size_t)(t + 2) * kstep; const char* b2 = last ? nB : cB + (size_t)(t + 2) * kstep;
;             const char* a3 = a2 + kstep; const char* b3 = b2 + kstep;
;             PG8_LDB(B0, 0, 0); PG8_LDB(B1, 0, 1); PG8_SCHED; PG8_LDA(At, 0, 0); PG8_STAGE(PG8_SA(1, 1), a1 + hstep, voffA);
;     ...
; #pragma unroll
;             for (int a = 0; a < 2; ++a)
; #pragma unroll
;                 for (int b = 0; b < 2; ++b)
; #pragma unroll
;                     for (int m = 0; m < 4; ++m)
; #pragma unroll
;                         for (int n = 0; n < 2; ++n) acc[a][b][m][n] = (f32x4){0.f, 0.f, 0.f, 0.f};
.LBB0_326:
	ds_read_b128 v[192:195], v164 offset:0
	ds_read_b128 v[196:199], v164 offset:1024
	ds_read_b128 v[200:203], v164 offset:2048
	ds_read_b128 v[204:207], v164 offset:3072
	ds_read_b128 v[208:211], v164 offset:4096
	ds_read_b128 v[212:215], v164 offset:5120
	ds_read_b128 v[216:219], v164 offset:6144
	ds_read_b128 v[220:223], v164 offset:7168
	ds_read_b128 v[128:131], v162 offset:0
	ds_read_b128 v[132:135], v162 offset:1024
	ds_read_b128 v[166:169], v162 offset:2048
	ds_read_b128 v[170:173], v162 offset:3072
	s_ashr_i32 s19, s18, 31
	s_lshl_b64 s[20:21], s[18:19], 20
	s_add_u32 s20, s4, s20
	s_addc_u32 s21, s5, s21
	v_readlane_b32 s52, v248, 29
	s_and_b64 s[22:23], s[0:1], exec
	v_readlane_b32 s53, v248, 30
	v_readlane_b32 s54, v248, 31
	v_readlane_b32 s55, v248, 32
	v_readlane_b32 s56, v248, 33
	v_readlane_b32 s57, v248, 34
	s_cselect_b32 s3, s21, s27
	s_cselect_b32 s19, s20, s26
	s_ashr_i32 s17, s16, 31
	v_readlane_b32 s58, v248, 35
	v_readlane_b32 s59, v248, 36
	s_mov_b64 s[52:53], s[56:57]
	s_lshl_b64 s[22:23], s[16:17], 20
	s_mov_b64 s[54:55], s[58:59]
	s_add_u32 s22, s54, s22
	s_addc_u32 s23, s55, s23
	s_and_b64 s[30:31], s[0:1], exec
	s_cselect_b32 s17, s23, s29
	s_cselect_b32 s25, s22, s28
	v_mov_b32_e32 v0, 0
	v_mov_b32_e32 v1, v0
	v_mov_b32_e32 v2, v0
	v_mov_b32_e32 v3, v0
	v_mov_b32_e32 v4, v0
	v_mov_b32_e32 v5, v0
	v_mov_b32_e32 v6, v0
	v_mov_b32_e32 v7, v0
	v_mov_b32_e32 v16, v0
	v_mov_b32_e32 v17, v0
	v_mov_b32_e32 v18, v0
	v_mov_b32_e32 v19, v0
	v_mov_b32_e32 v20, v0
	v_mov_b32_e32 v21, v0
	v_mov_b32_e32 v22, v0
	v_mov_b32_e32 v23, v0
	v_mov_b32_e32 v32, v0
	v_mov_b32_e32 v33, v0
	v_mov_b32_e32 v34, v0
	v_mov_b32_e32 v35, v0
	v_mov_b32_e32 v36, v0
	v_mov_b32_e32 v37, v0
	v_mov_b32_e32 v38, v0
	v_mov_b32_e32 v39, v0
	v_mov_b32_e32 v48, v0
	v_mov_b32_e32 v49, v0
	v_mov_b32_e32 v50, v0
	v_mov_b32_e32 v51, v0
	v_mov_b32_e32 v52, v0
	v_mov_b32_e32 v53, v0
	v_mov_b32_e32 v54, v0
	v_mov_b32_e32 v55, v0
	v_mov_b32_e32 v8, v0
	v_mov_b32_e32 v9, v0
	v_mov_b32_e32 v10, v0
	v_mov_b32_e32 v11, v0
	v_mov_b32_e32 v12, v0
	v_mov_b32_e32 v13, v0
	v_mov_b32_e32 v14, v0
	v_mov_b32_e32 v15, v0
	v_mov_b32_e32 v24, v0
	v_mov_b32_e32 v25, v0
	v_mov_b32_e32 v26, v0
	v_mov_b32_e32 v27, v0
	v_mov_b32_e32 v28, v0
	v_mov_b32_e32 v29, v0
	v_mov_b32_e32 v30, v0
	v_mov_b32_e32 v31, v0
	v_mov_b32_e32 v40, v0
	v_mov_b32_e32 v41, v0
	v_mov_b32_e32 v42, v0
	v_mov_b32_e32 v43, v0
	v_mov_b32_e32 v44, v0
	v_mov_b32_e32 v45, v0
	v_mov_b32_e32 v46, v0
	v_mov_b32_e32 v47, v0
	v_mov_b32_e32 v56, v0
	v_mov_b32_e32 v57, v0
	v_mov_b32_e32 v58, v0
	v_mov_b32_e32 v59, v0
	v_mov_b32_e32 v60, v0
	v_mov_b32_e32 v61, v0
	v_mov_b32_e32 v62, v0
	v_mov_b32_e32 v63, v0
	v_mov_b32_e32 v64, v0
	v_mov_b32_e32 v65, v0
	v_mov_b32_e32 v66, v0
	v_mov_b32_e32 v67, v0
	v_mov_b32_e32 v68, v0
	v_mov_b32_e32 v69, v0
	v_mov_b32_e32 v70, v0
	v_mov_b32_e32 v71, v0
	v_mov_b32_e32 v80, v0
	v_mov_b32_e32 v81, v0
	v_mov_b32_e32 v82, v0
	v_mov_b32_e32 v83, v0
	v_mov_b32_e32 v84, v0
	v_mov_b32_e32 v85, v0
	v_mov_b32_e32 v86, v0
	v_mov_b32_e32 v87, v0
	v_mov_b32_e32 v96, v0
	v_mov_b32_e32 v97, v0
	v_mov_b32_e32 v98, v0
	v_mov_b32_e32 v99, v0
	v_mov_b32_e32 v100, v0
	v_mov_b32_e32 v101, v0
	v_mov_b32_e32 v102, v0
	v_mov_b32_e32 v103, v0
	v_mov_b32_e32 v112, v0
	v_mov_b32_e32 v113, v0
	v_mov_b32_e32 v114, v0
	v_mov_b32_e32 v115, v0
	v_mov_b32_e32 v116, v0
	v_mov_b32_e32 v117, v0
	v_mov_b32_e32 v118, v0
	v_mov_b32_e32 v119, v0
	v_mov_b32_e32 v72, v0
	v_mov_b32_e32 v73, v0
	v_mov_b32_e32 v74, v0
	v_mov_b32_e32 v75, v0
	v_mov_b32_e32 v76, v0
	v_mov_b32_e32 v77, v0
	v_mov_b32_e32 v78, v0
	v_mov_b32_e32 v79, v0
	v_mov_b32_e32 v88, v0
	v_mov_b32_e32 v89, v0
	v_mov_b32_e32 v90, v0
	v_mov_b32_e32 v91, v0
	v_mov_b32_e32 v92, v0
	v_mov_b32_e32 v93, v0
	v_mov_b32_e32 v94, v0
	v_mov_b32_e32 v95, v0
	v_mov_b32_e32 v104, v0
	v_mov_b32_e32 v105, v0
	v_mov_b32_e32 v106, v0
	v_mov_b32_e32 v107, v0
	v_mov_b32_e32 v108, v0
	v_mov_b32_e32 v109, v0
	v_mov_b32_e32 v110, v0
	v_mov_b32_e32 v111, v0
	v_mov_b32_e32 v120, v0
	v_mov_b32_e32 v121, v0
	v_mov_b32_e32 v122, v0
	v_mov_b32_e32 v123, v0
	v_mov_b32_e32 v124, v0
	v_mov_b32_e32 v125, v0
	v_mov_b32_e32 v126, v0
	v_mov_b32_e32 v127, v0
	s_waitcnt lgkmcnt(0)
	s_barrier
	s_mov_b32 s80, 0
	.p2align 6
; #define PG8_STAGE(bufoff, gbase, voff) do { _Pragma("unroll") for (int _i = 0; _i < 2; ++_i) \
;         __builtin_amdgcn_global_load_lds((const unsigned*)((const char*)(gbase) + (voff)[_i]), (LAS unsigned*)(lds + (bufoff) + ldsw + _i * 8192), 16, 0, 0); } while (0)
; #define PG8_LDA(dst, b, h) do { _Pragma("unroll") for (int m = 0; m < 4; ++m) _Pragma("unroll") for (int k = 0; k < 2; ++k) dst[m][k] = *(const LAS bf16x8*)(lds + PG8_SA(b, h) + aoff + m * 2048 + k * 1024); } while (0)
; #define PG8_LDB(dst, b, h) do { _Pragma("unroll") for (int n = 0; n < 2; ++n) _Pragma("unroll") for (int k = 0; k < 2; ++k) dst[n][k] = *(const LAS bf16x8*)(lds + PG8_SB(b, h) + boff + n * 2048 + k * 1024); } while (0)
; #define PG8_MMA(ai, bj, At, Bt) do { __builtin_amdgcn_s_setprio(1); _Pragma("unroll") for (int m = 0; m < 4; ++m) _Pragma("unroll") for (int n = 0; n < 2; ++n) _Pragma("unroll") for (int k = 0; k < 2; ++k) \
;         acc[ai][bj][m][n] = __builtin_amdgcn_mfma_f32_16x16x32_bf16(Bt[n][k], At[m][k], acc[ai][bj][m][n], 0, 0, 0); __builtin_amdgcn_s_setprio(0); } while (0)
; #define PG8_WAIT_V(n) asm volatile("s_waitcnt vmcnt(" #n ")" ::: "memory")
; #define PG8_WAIT_L(n) asm volatile("s_waitcnt lgkmcnt(" #n ")" ::: "memory")
; #define PG8_BAR __builtin_amdgcn_s_barrier()
; template <class Epi, class Sched, int NSEG, bool ALIGN_EPI = true, bool AFTER_DRAIN = false>
; __device__ __forceinline__ void gemm_phase(LAS unsigned char* lds, const Gemm g, const Sched& S, const Epi& E) {
;     ...
;         for (int t = 0; t < nt; t += 2) {
;             const bool last = (t == nt - 2);
;             const char* a1 = cA + (size_t)(t + 1) * kstep;
;             const char* a2 = last ? nA : cA + (size_t)(t + 2) * kstep; const char* b2 = last ? nB : cB + (size_t)(t + 2) * kstep;
;             const char* a3 = a2 + kstep; const char* b3 = b2 + kstep;
;             PG8_LDB(B0, 0, 0); PG8_LDB(B1, 0, 1); PG8_SCHED; PG8_LDA(At, 0, 0); PG8_STAGE(PG8_SA(1, 1), a1 + hstep, voffA);
;             PG8_WAIT_V(8); PG8_WAIT_L(0); PG8_BAR; PG8_MMA(0, 0, At, B0); PG8_MMA(0, 1, At, B1); PG8_BAR; PG8_SCHED;
;             PG8_LDA(At, 0, 1); PG8_STAGE(PG8_SB(0, 0), b2, voffB); PG8_STAGE(PG8_SB(0, 1), b2 + hstep, voffB); PG8_STAGE(PG8_SA(0, 0), a2, voffA);
;             PG8_WAIT_V(8); PG8_WAIT_L(0); PG8_BAR; PG8_MMA(1, 0, At, B0); PG8_MMA(1, 1, At, B1); PG8_BAR; PG8_SCHED;
.Lp1_kloop:
	s_cmp_eq_u32 s80, 15
	s_cselect_b32 s72, s19, s72
	s_cselect_b32 s73, s3, s73
	s_cselect_b32 s76, s25, s76
	s_cselect_b32 s77, s17, s77
	s_add_u32 s74, s72, 0x80000
	s_addc_u32 s75, s73, 0
	s_add_u32 s78, s76, 0x80000
	s_addc_u32 s79, s77, 0
	v_mfma_f32_16x16x32_bf16 v[124:127], v[128:131], v[192:195], v[124:127]
	ds_read_b128 v[174:177], v162 offset:16384
	v_mfma_f32_16x16x32_bf16 v[120:123], v[166:169], v[192:195], v[120:123]
	ds_read_b128 v[178:181], v162 offset:17408
	v_mfma_f32_16x16x32_bf16 v[108:111], v[128:131], v[200:203], v[108:111]
	ds_read_b128 v[182:185], v162 offset:18432
	v_mfma_f32_16x16x32_bf16 v[104:107], v[166:169], v[200:203], v[104:107]
	ds_read_b128 v[188:191], v162 offset:19456
	v_mfma_f32_16x16x32_bf16 v[92:95], v[128:131], v[208:211], v[92:95]
	s_mov_b32 m0, s33
	v_mfma_f32_16x16x32_bf16 v[88:91], v[166:169], v[208:211], v[88:91]
	global_load_lds_dwordx4 v138, s[72:73]
	v_mfma_f32_16x16x32_bf16 v[76:79], v[128:131], v[216:219], v[76:79]
	ds_read_b128 v[224:227], v164 offset:16384
	v_mfma_f32_16x16x32_bf16 v[72:75], v[166:169], v[216:219], v[72:75]
	ds_read_b128 v[228:231], v164 offset:17408
	v_mfma_f32_16x16x32_bf16 v[124:127], v[132:135], v[196:199], v[124:127]
	ds_read_b128 v[232:235], v164 offset:18432
	v_mfma_f32_16x16x32_bf16 v[120:123], v[170:173], v[196:199], v[120:123]
	ds_read_b128 v[236:239], v164 offset:19456
	v_mfma_f32_16x16x32_bf16 v[108:111], v[132:135], v[204:207], v[108:111]
	s_add_i32 m0, s33, 0x2000
	v_mfma_f32_16x16x32_bf16 v[104:107], v[170:173], v[204:207], v[104:107]
	global_load_lds_dwordx4 v142, s[72:73]
	v_mfma_f32_16x16x32_bf16 v[92:95], v[132:135], v[212:215], v[92:95]
	ds_read_b128 v[240:243], v164 offset:20480
	v_mfma_f32_16x16x32_bf16 v[88:91], v[170:173], v[212:215], v[88:91]
	ds_read_b128 v[244:247], v164 offset:21504
	v_mfma_f32_16x16x32_bf16 v[76:79], v[132:135], v[220:223], v[76:79]
	ds_read_b128 v[250:253], v164 offset:22528
	v_mfma_f32_16x16x32_bf16 v[72:75], v[170:173], v[220:223], v[72:75]
	ds_read_b128 v[150:153], v164 offset:23552
	s_waitcnt lgkmcnt(8)
	v_mfma_f32_16x16x32_bf16 v[116:119], v[174:177], v[192:195], v[116:119]
	s_add_i32 m0, s33, 0x10000
	v_mfma_f32_16x16x32_bf16 v[112:115], v[182:185], v[192:195], v[112:115]
	global_load_lds_dwordx4 v140, s[76:77]
	v_mfma_f32_16x16x32_bf16 v[100:103], v[174:177], v[200:203], v[100:103]
	v_mfma_f32_16x16x32_bf16 v[96:99], v[182:185], v[200:203], v[96:99]
	v_mfma_f32_16x16x32_bf16 v[84:87], v[174:177], v[208:211], v[84:87]
	s_add_i32 m0, s33, 0x12000
	v_mfma_f32_16x16x32_bf16 v[80:83], v[182:185], v[208:211], v[80:83]
	global_load_lds_dwordx4 v144, s[76:77]
	v_mfma_f32_16x16x32_bf16 v[68:71], v[174:177], v[216:219], v[68:71]
	v_mfma_f32_16x16x32_bf16 v[64:67], v[182:185], v[216:219], v[64:67]
	v_mfma_f32_16x16x32_bf16 v[116:119], v[178:181], v[196:199], v[116:119]
	v_mfma_f32_16x16x32_bf16 v[112:115], v[188:191], v[196:199], v[112:115]
	v_mfma_f32_16x16x32_bf16 v[100:103], v[178:181], v[204:207], v[100:103]
	v_mfma_f32_16x16x32_bf16 v[96:99], v[188:191], v[204:207], v[96:99]
	v_mfma_f32_16x16x32_bf16 v[84:87], v[178:181], v[212:215], v[84:87]
	v_mfma_f32_16x16x32_bf16 v[80:83], v[188:191], v[212:215], v[80:83]
	v_mfma_f32_16x16x32_bf16 v[68:71], v[178:181], v[220:223], v[68:71]
	v_mfma_f32_16x16x32_bf16 v[64:67], v[188:191], v[220:223], v[64:67]
	s_waitcnt vmcnt(8) lgkmcnt(0)
	s_barrier
	v_mfma_f32_16x16x32_bf16 v[60:63], v[128:131], v[224:227], v[60:63]
	ds_read_b128 v[192:195], v164 offset:32768
	v_mfma_f32_16x16x32_bf16 v[56:59], v[166:169], v[224:227], v[56:59]
	ds_read_b128 v[196:199], v164 offset:33792
	v_mfma_f32_16x16x32_bf16 v[44:47], v[128:131], v[232:235], v[44:47]
	ds_read_b128 v[200:203], v164 offset:34816
	v_mfma_f32_16x16x32_bf16 v[40:43], v[166:169], v[232:235], v[40:43]
	ds_read_b128 v[204:207], v164 offset:35840
	v_mfma_f32_16x16x32_bf16 v[28:31], v[128:131], v[240:243], v[28:31]
	ds_read_b128 v[208:211], v164 offset:36864
	v_mfma_f32_16x16x32_bf16 v[24:27], v[166:169], v[240:243], v[24:27]
	ds_read_b128 v[212:215], v164 offset:37888
	v_mfma_f32_16x16x32_bf16 v[12:15], v[128:131], v[250:253], v[12:15]
	ds_read_b128 v[216:219], v164 offset:38912
	v_mfma_f32_16x16x32_bf16 v[8:11], v[166:169], v[250:253], v[8:11]
	ds_read_b128 v[220:223], v164 offset:39936
	v_mfma_f32_16x16x32_bf16 v[60:63], v[132:135], v[228:231], v[60:63]
	s_add_i32 m0, s33, 0x4000
	v_mfma_f32_16x16x32_bf16 v[56:59], v[170:173], v[228:231], v[56:59]
	global_load_lds_dwordx4 v138, s[74:75]
	v_mfma_f32_16x16x32_bf16 v[44:47], v[132:135], v[236:239], v[44:47]
	v_mfma_f32_16x16x32_bf16 v[40:43], v[170:173], v[236:239], v[40:43]
	v_mfma_f32_16x16x32_bf16 v[28:31], v[132:135], v[244:247], v[28:31]
	s_add_i32 m0, s33, 0x6000
	v_mfma_f32_16x16x32_bf16 v[24:27], v[170:173], v[244:247], v[24:27]
	global_load_lds_dwordx4 v142, s[74:75]
	v_mfma_f32_16x16x32_bf16 v[12:15], v[132:135], v[150:153], v[12:15]
	v_mfma_f32_16x16x32_bf16 v[8:11], v[170:173], v[150:153], v[8:11]
	v_mfma_f32_16x16x32_bf16 v[52:55], v[174:177], v[224:227], v[52:55]
	ds_read_b128 v[128:131], v162 offset:32768
	v_mfma_f32_16x16x32_bf16 v[48:51], v[182:185], v[224:227], v[48:51]
	ds_read_b128 v[132:135], v162 offset:33792
	v_mfma_f32_16x16x32_bf16 v[36:39], v[174:177], v[232:235], v[36:39]
	ds_read_b128 v[166:169], v162 offset:34816
	v_mfma_f32_16x16x32_bf16 v[32:35], v[182:185], v[232:235], v[32:35]
	ds_read_b128 v[170:173], v162 offset:35840
	v_mfma_f32_16x16x32_bf16 v[20:23], v[174:177], v[240:243], v[20:23]
	s_add_i32 m0, s33, 0x14000
	v_mfma_f32_16x16x32_bf16 v[16:19], v[182:185], v[240:243], v[16:19]
	global_load_lds_dwordx4 v140, s[78:79]
	v_mfma_f32_16x16x32_bf16 v[4:7], v[174:177], v[250:253], v[4:7]
	v_mfma_f32_16x16x32_bf16 v[0:3], v[182:185], v[250:253], v[0:3]
	v_mfma_f32_16x16x32_bf16 v[52:55], v[178:181], v[228:231], v[52:55]
	s_add_i32 m0, s33, 0x16000
	v_mfma_f32_16x16x32_bf16 v[48:51], v[188:191], v[228:231], v[48:51]
	global_load_lds_dwordx4 v144, s[78:79]
	v_mfma_f32_16x16x32_bf16 v[36:39], v[178:181], v[236:239], v[36:39]
	v_mfma_f32_16x16x32_bf16 v[32:35], v[188:191], v[236:239], v[32:35]
	v_mfma_f32_16x16x32_bf16 v[20:23], v[178:181], v[244:247], v[20:23]
	v_mfma_f32_16x16x32_bf16 v[16:19], v[188:191], v[244:247], v[16:19]
	v_mfma_f32_16x16x32_bf16 v[4:7], v[178:181], v[150:153], v[4:7]
	v_mfma_f32_16x16x32_bf16 v[0:3], v[188:191], v[150:153], v[0:3]
	s_waitcnt vmcnt(8) lgkmcnt(0)
	s_barrier
; #define PG8_STAGE(bufoff, gbase, voff) do { _Pragma("unroll") for (int _i = 0; _i < 2; ++_i) \
;         __builtin_amdgcn_global_load_lds((const unsigned*)((const char*)(gbase) + (voff)[_i]), (LAS unsigned*)(lds + (bufoff) + ldsw + _i * 8192), 16, 0, 0); } while (0)
; #define PG8_LDA(dst, b, h) do { _Pragma("unroll") for (int m = 0; m < 4; ++m) _Pragma("unroll") for (int k = 0; k < 2; ++k) dst[m][k] = *(const LAS bf16x8*)(lds + PG8_SA(b, h) + aoff + m * 2048 + k * 1024); } while (0)
; #define PG8_LDB(dst, b, h) do { _Pragma("unroll") for (int n = 0; n < 2; ++n) _Pragma("unroll") for (int k = 0; k < 2; ++k) dst[n][k] = *(const LAS bf16x8*)(lds + PG8_SB(b, h) + boff + n * 2048 + k * 1024); } while (0)
; #define PG8_BAR __builtin_amdgcn_s_barrier()
; template <class Epi, class Sched, int NSEG, bool ALIGN_EPI = true, bool AFTER_DRAIN = false>
; __device__ __forceinline__ void gemm_phase(LAS unsigned char* lds, const Gemm g, const Sched& S, const Epi& E) {
;     ...
;             const bool last = (t == nt - 2);
;             const char* a1 = cA + (size_t)(t + 1) * kstep;
;             const char* a2 = last ? nA : cA + (size_t)(t + 2) * kstep; const char* b2 = last ? nB : cB + (size_t)(t + 2) * kstep;
;             const char* a3 = a2 + kstep; const char* b3 = b2 + kstep;
;             PG8_LDB(B0, 0, 0); PG8_LDB(B1, 0, 1); PG8_SCHED; PG8_LDA(At, 0, 0); PG8_STAGE(PG8_SA(1, 1), a1 + hstep, voffA);
;             PG8_WAIT_V(8); PG8_WAIT_L(0); PG8_BAR; PG8_MMA(0, 0, At, B0); PG8_MMA(0, 1, At, B1); PG8_BAR; PG8_SCHED;
;             PG8_LDA(At, 0, 1); PG8_STAGE(PG8_SB(0, 0), b2, voffB); PG8_STAGE(PG8_SB(0, 1), b2 + hstep, voffB); PG8_STAGE(PG8_SA(0, 0), a2, voffA);
;             PG8_WAIT_V(8); PG8_WAIT_L(0); PG8_BAR; PG8_MMA(1, 0, At, B0); PG8_MMA(1, 1, At, B1); PG8_BAR; PG8_SCHED;
;             PG8_LDB(B0, 1, 0); PG8_LDB(B1, 1, 1); PG8_SCHED; PG8_LDA(At, 1, 0); PG8_STAGE(PG8_SA(0, 1), a2 + hstep, voffA);
;             PG8_WAIT_V(8); PG8_WAIT_L(0); PG8_BAR; PG8_MMA(0, 0, At, B0); PG8_MMA(0, 1, At, B1); PG8_BAR; PG8_SCHED;
;             PG8_LDA(At, 1, 1); PG8_STAGE(PG8_SB(1, 0), b3, voffB); PG8_STAGE(PG8_SB(1, 1), b3 + hstep, voffB); PG8_STAGE(PG8_SA(1, 0), a3, voffA);
;             PG8_WAIT_V(8); PG8_WAIT_L(0); PG8_BAR; PG8_MMA(1, 0, At, B0); PG8_MMA(1, 1, At, B1); PG8_BAR; PG8_SCHED;
;         }
;         if constexpr (ALIGN_EPI) { if (wr == 0) PG8_BAR; }
	v_mfma_f32_16x16x32_bf16 v[124:127], v[128:131], v[192:195], v[124:127]
	ds_read_b128 v[174:177], v162 offset:49152
	s_add_u32 s72, s72, 0x80
	s_addc_u32 s73, s73, 0
	v_mfma_f32_16x16x32_bf16 v[120:123], v[166:169], v[192:195], v[120:123]
	ds_read_b128 v[178:181], v162 offset:50176
	s_add_u32 s76, s76, 0x80
	s_addc_u32 s77, s77, 0
	v_mfma_f32_16x16x32_bf16 v[108:111], v[128:131], v[200:203], v[108:111]
	ds_read_b128 v[182:185], v162 offset:51200
	v_mfma_f32_16x16x32_bf16 v[104:107], v[166:169], v[200:203], v[104:107]
	ds_read_b128 v[188:191], v162 offset:52224
	v_mfma_f32_16x16x32_bf16 v[92:95], v[128:131], v[208:211], v[92:95]
	s_add_i32 m0, s33, 0x8000
	v_mfma_f32_16x16x32_bf16 v[88:91], v[166:169], v[208:211], v[88:91]
	global_load_lds_dwordx4 v138, s[72:73]
	v_mfma_f32_16x16x32_bf16 v[76:79], v[128:131], v[216:219], v[76:79]
	ds_read_b128 v[224:227], v164 offset:49152
	v_mfma_f32_16x16x32_bf16 v[72:75], v[166:169], v[216:219], v[72:75]
	ds_read_b128 v[228:231], v164 offset:50176
	v_mfma_f32_16x16x32_bf16 v[124:127], v[132:135], v[196:199], v[124:127]
	ds_read_b128 v[232:235], v164 offset:51200
	v_mfma_f32_16x16x32_bf16 v[120:123], v[170:173], v[196:199], v[120:123]
	ds_read_b128 v[236:239], v164 offset:52224
	v_mfma_f32_16x16x32_bf16 v[108:111], v[132:135], v[204:207], v[108:111]
	s_add_i32 m0, s33, 0xa000
	v_mfma_f32_16x16x32_bf16 v[104:107], v[170:173], v[204:207], v[104:107]
	global_load_lds_dwordx4 v142, s[72:73]
	v_mfma_f32_16x16x32_bf16 v[92:95], v[132:135], v[212:215], v[92:95]
	ds_read_b128 v[240:243], v164 offset:53248
	v_mfma_f32_16x16x32_bf16 v[88:91], v[170:173], v[212:215], v[88:91]
	ds_read_b128 v[244:247], v164 offset:54272
	v_mfma_f32_16x16x32_bf16 v[76:79], v[132:135], v[220:223], v[76:79]
	ds_read_b128 v[250:253], v164 offset:55296
	v_mfma_f32_16x16x32_bf16 v[72:75], v[170:173], v[220:223], v[72:75]
	ds_read_b128 v[150:153], v164 offset:56320
	s_waitcnt lgkmcnt(8)
	v_mfma_f32_16x16x32_bf16 v[116:119], v[174:177], v[192:195], v[116:119]
	s_add_i32 m0, s33, 0x18000
	v_mfma_f32_16x16x32_bf16 v[112:115], v[182:185], v[192:195], v[112:115]
	global_load_lds_dwordx4 v140, s[76:77]
	v_mfma_f32_16x16x32_bf16 v[100:103], v[174:177], v[200:203], v[100:103]
	v_mfma_f32_16x16x32_bf16 v[96:99], v[182:185], v[200:203], v[96:99]
	v_mfma_f32_16x16x32_bf16 v[84:87], v[174:177], v[208:211], v[84:87]
	s_add_i32 m0, s33, 0x1a000
	v_mfma_f32_16x16x32_bf16 v[80:83], v[182:185], v[208:211], v[80:83]
	global_load_lds_dwordx4 v144, s[76:77]
	v_mfma_f32_16x16x32_bf16 v[68:71], v[174:177], v[216:219], v[68:71]
	v_mfma_f32_16x16x32_bf16 v[64:67], v[182:185], v[216:219], v[64:67]
	v_mfma_f32_16x16x32_bf16 v[116:119], v[178:181], v[196:199], v[116:119]
	s_add_u32 s74, s74, 0x80
	s_addc_u32 s75, s75, 0
	v_mfma_f32_16x16x32_bf16 v[112:115], v[188:191], v[196:199], v[112:115]
	s_add_u32 s78, s78, 0x80
	s_addc_u32 s79, s79, 0
	v_mfma_f32_16x16x32_bf16 v[100:103], v[178:181], v[204:207], v[100:103]
	v_mfma_f32_16x16x32_bf16 v[96:99], v[188:191], v[204:207], v[96:99]
	v_mfma_f32_16x16x32_bf16 v[84:87], v[178:181], v[212:215], v[84:87]
	v_mfma_f32_16x16x32_bf16 v[80:83], v[188:191], v[212:215], v[80:83]
	v_mfma_f32_16x16x32_bf16 v[68:71], v[178:181], v[220:223], v[68:71]
	v_mfma_f32_16x16x32_bf16 v[64:67], v[188:191], v[220:223], v[64:67]
	s_waitcnt vmcnt(8) lgkmcnt(0)
	s_barrier
	v_mfma_f32_16x16x32_bf16 v[60:63], v[128:131], v[224:227], v[60:63]
	ds_read_b128 v[192:195], v164 offset:0
	v_mfma_f32_16x16x32_bf16 v[56:59], v[166:169], v[224:227], v[56:59]
	ds_read_b128 v[196:199], v164 offset:1024
	v_mfma_f32_16x16x32_bf16 v[44:47], v[128:131], v[232:235], v[44:47]
	ds_read_b128 v[200:203], v164 offset:2048
	v_mfma_f32_16x16x32_bf16 v[40:43], v[166:169], v[232:235], v[40:43]
	ds_read_b128 v[204:207], v164 offset:3072
	v_mfma_f32_16x16x32_bf16 v[28:31], v[128:131], v[240:243], v[28:31]
	ds_read_b128 v[208:211], v164 offset:4096
	v_mfma_f32_16x16x32_bf16 v[24:27], v[166:169], v[240:243], v[24:27]
	ds_read_b128 v[212:215], v164 offset:5120
	v_mfma_f32_16x16x32_bf16 v[12:15], v[128:131], v[250:253], v[12:15]
	ds_read_b128 v[216:219], v164 offset:6144
	v_mfma_f32_16x16x32_bf16 v[8:11], v[166:169], v[250:253], v[8:11]
	ds_read_b128 v[220:223], v164 offset:7168
	v_mfma_f32_16x16x32_bf16 v[60:63], v[132:135], v[228:231], v[60:63]
	s_add_i32 m0, s33, 0xc000
	v_mfma_f32_16x16x32_bf16 v[56:59], v[170:173], v[228:231], v[56:59]
	global_load_lds_dwordx4 v138, s[74:75]
	v_mfma_f32_16x16x32_bf16 v[44:47], v[132:135], v[236:239], v[44:47]
	v_mfma_f32_16x16x32_bf16 v[40:43], v[170:173], v[236:239], v[40:43]
	v_mfma_f32_16x16x32_bf16 v[28:31], v[132:135], v[244:247], v[28:31]
	s_add_i32 m0, s33, 0xe000
	v_mfma_f32_16x16x32_bf16 v[24:27], v[170:173], v[244:247], v[24:27]
	global_load_lds_dwordx4 v142, s[74:75]
	v_mfma_f32_16x16x32_bf16 v[12:15], v[132:135], v[150:153], v[12:15]
	v_mfma_f32_16x16x32_bf16 v[8:11], v[170:173], v[150:153], v[8:11]
	v_mfma_f32_16x16x32_bf16 v[52:55], v[174:177], v[224:227], v[52:55]
	ds_read_b128 v[128:131], v162 offset:0
	v_mfma_f32_16x16x32_bf16 v[48:51], v[182:185], v[224:227], v[48:51]
	ds_read_b128 v[132:135], v162 offset:1024
	v_mfma_f32_16x16x32_bf16 v[36:39], v[174:177], v[232:235], v[36:39]
	ds_read_b128 v[166:169], v162 offset:2048
	v_mfma_f32_16x16x32_bf16 v[32:35], v[182:185], v[232:235], v[32:35]
	ds_read_b128 v[170:173], v162 offset:3072
	v_mfma_f32_16x16x32_bf16 v[20:23], v[174:177], v[240:243], v[20:23]
	s_add_i32 m0, s33, 0x1c000
	v_mfma_f32_16x16x32_bf16 v[16:19], v[182:185], v[240:243], v[16:19]
	global_load_lds_dwordx4 v140, s[78:79]
	v_mfma_f32_16x16x32_bf16 v[4:7], v[174:177], v[250:253], v[4:7]
	v_mfma_f32_16x16x32_bf16 v[0:3], v[182:185], v[250:253], v[0:3]
	v_mfma_f32_16x16x32_bf16 v[52:55], v[178:181], v[228:231], v[52:55]
	s_add_i32 m0, s33, 0x1e000
	v_mfma_f32_16x16x32_bf16 v[48:51], v[188:191], v[228:231], v[48:51]
	global_load_lds_dwordx4 v144, s[78:79]
	v_mfma_f32_16x16x32_bf16 v[36:39], v[178:181], v[236:239], v[36:39]
	v_mfma_f32_16x16x32_bf16 v[32:35], v[188:191], v[236:239], v[32:35]
	s_add_u32 s72, s72, 0x80
	s_addc_u32 s73, s73, 0
	v_mfma_f32_16x16x32_bf16 v[20:23], v[178:181], v[244:247], v[20:23]
	s_add_u32 s76, s76, 0x80
	s_addc_u32 s77, s77, 0
	v_mfma_f32_16x16x32_bf16 v[16:19], v[188:191], v[244:247], v[16:19]
	s_add_i32 s80, s80, 1
	v_mfma_f32_16x16x32_bf16 v[4:7], v[178:181], v[150:153], v[4:7]
	v_mfma_f32_16x16x32_bf16 v[0:3], v[188:191], v[150:153], v[0:3]
	s_waitcnt vmcnt(8) lgkmcnt(0)
	s_barrier
	s_cmp_lt_u32 s80, 16
	s_cbranch_scc1 .Lp1_kloop
	s_nop 7
	s_and_b64 vcc, exec, s[12:13]
	s_cbranch_vccz .LBB0_331
	s_cmp_gt_i32 s2, 31
	s_mov_b64 s[26:27], -1
	s_cbranch_scc1 .LBB0_332

; #define PG8_BAR __builtin_amdgcn_s_barrier()
; template <class Epi, class Sched, int NSEG, bool ALIGN_EPI = true, bool AFTER_DRAIN = false>
; __device__ __forceinline__ void gemm_phase(LAS unsigned char* lds, const Gemm g, const Sched& S, const Epi& E) {
;     ...
;         if (!has_next) break;
;         if (!midseg) {
; #pragma unroll
;             for (int a = 0; a < 2; ++a)
; #pragma unroll
;                 for (int b = 0; b < 2; ++b)
; #pragma unroll
;                     for (int m = 0; m < 4; ++m)
; #pragma unroll
;                         for (int n = 0; n < 2; ++n) acc[a][b][m][n] = (f32x4){0.f, 0.f, 0.f, 0.f};
;         }
;         cur = nxt; cA = nA; cB = nB; ++ui;
;         if constexpr (ALIGN_EPI) { if (wr == 1) PG8_BAR; }
;     }
.LBB0_409:
	s_andn2_b64 vcc, exec, s[0:1]
	s_mov_b64 s[0:1], -1
	s_cbranch_vccnz .LBB0_323
	s_andn2_b64 vcc, exec, s[8:9]
	s_cbranch_vccnz .LBB0_322
	s_branch .LBB0_322

; #define LAS __attribute__((address_space(3)))
; __device__ __forceinline__ unsigned cvt_pk_bf16(float lo, float hi) { unsigned r; asm volatile("v_cvt_pk_bf16_f32 %0, %1, %2" : "=v"(r) : "v"(lo), "v"(hi)); return r; }
; __device__ __forceinline__ float bf_lo(unsigned w) { return __uint_as_float(w << 16); }
; __device__ __forceinline__ float bf_hi(unsigned w) { return __uint_as_float(w & 0xffff0000u); }
; __device__ __forceinline__ int crow(int r, int hi) { return (r & 3) + 8 * (r >> 2) + 4 * hi; }
; __device__ __forceinline__ void fox_block(const BlockRef& cur, const BlockRef& nxt, char* lds, Seam& S, const int tid) {
;     ...
;     if (hi == 0) li_l[r32] = l_reg; asm volatile("s_waitcnt lgkmcnt(0)" ::: "memory");
;     float rli[16];
; #pragma unroll
;     for (int r = 0; r < 16; ++r) rli[r] = __builtin_amdgcn_rcpf(li_l[crow(r, hi)]);
;     typedef __attribute__((address_space(1))) bf16_t gbf16; typedef __attribute__((address_space(1))) u32x4 gu32x4;
;     LAS float* stg = (LAS float*)(lds3 + SLOT + wid * 4096);
;     const int er = lane >> 2, eq = lane & 3;
;     gbf16* obase = (gbf16*)(cur.O + (size_t)(wid * QBLK + er) * LD + 8 * eq); const gbf16* zbase = (const gbf16*)(cur.Z + (size_t)(wid * QBLK + er) * LD + 8 * eq);
; #pragma unroll
;     for (int d0 = 0; d0 < 4; ++d0) {
; #pragma unroll
;         for (int r = 0; r < 16; ++r) stg[crow(r, hi) * 32 + r32] = o[d0][r] * rli[r];
;         asm volatile("s_waitcnt lgkmcnt(0)" ::: "memory");
;         gbf16* op = obase; const gbf16* zp = zbase;
; #pragma unroll
;         for (int i = 0; i < 2; ++i) {
;             asm volatile("" : "+v"(op), "+v"(zp));
;             const f32x4 v0 = *(const LAS f32x4*)(stg + (er + 16 * i) * 32 + 8 * eq), v1 = *(const LAS f32x4*)(stg + (er + 16 * i) * 32 + 8 * eq + 4);
;             const u32x4 z = __builtin_nontemporal_load((const gu32x4*)(zp + d0 * 32));
;             u32x4 w; w.x = cvt_pk_bf16(v0.x * bf_lo(z.x), v0.y * bf_hi(z.x)); w.y = cvt_pk_bf16(v0.z * bf_lo(z.y), v0.w * bf_hi(z.y));
;             w.z = cvt_pk_bf16(v1.x * bf_lo(z.z), v1.y * bf_hi(z.z)); w.w = cvt_pk_bf16(v1.z * bf_lo(z.w), v1.w * bf_hi(z.w));
;             *(gu32x4*)(op + d0 * 32) = w;
;             op += 16 * LD; zp += 16 * LD; }
;         asm volatile("s_waitcnt lgkmcnt(0)" ::: "memory"); }
.LBB0_485:
	s_or_b64 exec, exec, s[2:3]
	s_waitcnt lgkmcnt(0)
	ds_read_b128 v[64:67], v131
	ds_read_b128 v[68:71], v131 offset:32
	v_readlane_b32 s0, v248, 54
	s_add_u32 s0, s0, s68
	v_readlane_b32 s1, v248, 56
	s_waitcnt lgkmcnt(0)
	v_rcp_f32_e32 v72, v64
	v_rcp_f32_e32 v73, v65
	v_rcp_f32_e32 v74, v66
	v_rcp_f32_e32 v75, v67
	v_rcp_f32_e32 v76, v68
	ds_read_b128 v[64:67], v131 offset:64
	v_rcp_f32_e32 v77, v69
	v_rcp_f32_e32 v78, v70
	v_rcp_f32_e32 v79, v71
	ds_read_b128 v[68:71], v131 offset:96
	s_addc_u32 s1, s1, s69
	v_readlane_b32 s2, v248, 42
	s_add_u32 s2, s2, s68
	v_readlane_b32 s3, v248, 43
	s_addc_u32 s3, s3, s69
	s_lshl_b32 s4, s70, 12
	s_add_i32 s4, s4, 0
	s_waitcnt lgkmcnt(0)
	v_rcp_f32_e32 v84, v68
	v_add3_u32 v68, s4, v133, v170
	v_rcp_f32_e32 v80, v64
	v_rcp_f32_e32 v81, v65
	v_mul_f32_e32 v48, v48, v72
	v_mul_f32_e32 v49, v49, v73
	v_add_u32_e32 v88, 0x4000, v68
	v_rcp_f32_e32 v82, v66
	v_rcp_f32_e32 v83, v67
	ds_write2_b32 v88, v48, v49 offset1:32
	v_mul_f32_e32 v48, v50, v74
	v_mul_f32_e32 v49, v51, v75
	v_rcp_f32_e32 v85, v69
	ds_write2_b32 v88, v48, v49 offset0:64 offset1:96
	v_mul_f32_e32 v48, v52, v76
	v_mul_f32_e32 v49, v53, v77
	v_add_u32_e32 v89, 0x4400, v68
	v_rcp_f32_e32 v86, v70
	v_rcp_f32_e32 v87, v71
	v_or_b32_e32 v64, s71, v191
	ds_write2_b32 v89, v48, v49 offset1:32
	v_mul_f32_e32 v48, v54, v78
	v_mul_f32_e32 v49, v55, v79
	v_ashrrev_i32_e32 v65, 31, v64
	ds_write2_b32 v89, v48, v49 offset0:64 offset1:96
	v_mul_f32_e32 v48, v56, v80
	v_mul_f32_e32 v49, v57, v81
	v_add_u32_e32 v90, 0x4800, v68
	v_lshlrev_b64 v[66:67], 12, v[64:65]
	ds_write2_b32 v90, v48, v49 offset1:32
	v_mul_f32_e32 v48, v58, v82
	v_mul_f32_e32 v49, v59, v83
	v_lshl_add_u64 v[64:65], s[0:1], 0, v[66:67]
	v_lshlrev_b32_e32 v128, 1, v132
	v_lshl_add_u64 v[66:67], s[2:3], 0, v[66:67]
	ds_write2_b32 v90, v48, v49 offset0:64 offset1:96
	v_mul_f32_e32 v48, v60, v84
	v_mul_f32_e32 v49, v61, v85
	v_add_u32_e32 v91, 0x4c00, v68
	v_lshl_add_u64 v[64:65], v[64:65], 0, v[128:129]
	v_lshl_add_u64 v[66:67], v[66:67], 0, v[128:129]
	ds_write2_b32 v91, v48, v49 offset1:32
	v_mul_f32_e32 v48, v62, v86
	v_mul_f32_e32 v49, v63, v87
	ds_write2_b32 v91, v48, v49 offset0:64 offset1:96
	v_mov_b64_e32 v[62:63], v[64:65]
	v_mov_b64_e32 v[68:69], v[66:67]
	s_waitcnt lgkmcnt(0)
	global_load_dwordx4 v[50:53], v[68:69], off nt
	v_add_co_u32_e32 v250, vcc, 0x10000, v68
	s_nop 1
	v_addc_co_u32_e32 v251, vcc, 0, v69, vcc
	global_load_dwordx4 v[222:225], v[250:251], off nt
	global_load_dwordx4 v[226:229], v[68:69], off offset:64 nt
	global_load_dwordx4 v[230:233], v[250:251], off offset:64 nt
	global_load_dwordx4 v[234:237], v[68:69], off offset:128 nt
	global_load_dwordx4 v[238:241], v[250:251], off offset:128 nt
	global_load_dwordx4 v[242:245], v[68:69], off offset:192 nt
	v_lshlrev_b32_e32 v48, 2, v132
	v_add3_u32 v48, s4, v48, v145
	ds_read_b128 v[54:57], v48 offset:16384
	ds_read_b128 v[58:61], v48 offset:16400
	s_mov_b64 s[0:1], 0x10000
	v_lshl_add_u64 v[70:71], v[62:63], 0, s[0:1]
	v_lshl_add_u64 v[68:69], v[68:69], 0, s[0:1]
	v_mul_f32_e32 v40, v40, v80
	v_mul_f32_e32 v41, v41, v81
	v_mul_f32_e32 v42, v42, v82
	v_mul_f32_e32 v43, v43, v83
	v_mul_f32_e32 v44, v44, v84
	v_mul_f32_e32 v45, v45, v85
	v_mul_f32_e32 v46, v46, v86
	v_mul_f32_e32 v47, v47, v87
	v_mul_f32_e32 v24, v24, v80
	v_mul_f32_e32 v25, v25, v81
	v_mul_f32_e32 v26, v26, v82
	v_mul_f32_e32 v27, v27, v83
	v_mul_f32_e32 v28, v28, v84
	v_mul_f32_e32 v29, v29, v85
	v_mul_f32_e32 v30, v30, v86
	v_mul_f32_e32 v31, v31, v87
	v_mul_f32_e32 v8, v8, v80
	v_mul_f32_e32 v9, v9, v81
	v_mul_f32_e32 v10, v10, v82
	v_mul_f32_e32 v11, v11, v83
	v_mul_f32_e32 v12, v12, v84
	v_mul_f32_e32 v13, v13, v85
	v_mul_f32_e32 v14, v14, v86
	v_mul_f32_e32 v15, v15, v87
	v_readlane_b32 s60, v247, 11
	s_add_i32 s60, s60, s96
	v_readlane_b32 s66, v247, 4
	v_readlane_b32 s68, v247, 6
	s_movk_i32 s6, 0x1010
	v_readlane_b32 s67, v247, 5
	v_readlane_b32 s69, v247, 7
	s_waitcnt vmcnt(6)
	v_lshlrev_b32_e32 v49, 16, v50
	v_and_b32_e32 v50, 0xffff0000, v50
	v_lshlrev_b32_e32 v92, 16, v51
	v_and_b32_e32 v51, 0xffff0000, v51
	v_lshlrev_b32_e32 v93, 16, v52
	v_and_b32_e32 v52, 0xffff0000, v52
	v_lshlrev_b32_e32 v94, 16, v53
	v_and_b32_e32 v53, 0xffff0000, v53
	s_waitcnt lgkmcnt(1)
	v_mul_f32_e32 v50, v55, v50
	v_mul_f32_e32 v51, v57, v51
	s_waitcnt lgkmcnt(0)
	v_mul_f32_e32 v52, v59, v52
	v_mul_f32_e32 v53, v61, v53
	v_mul_f32_e32 v49, v54, v49
	v_mul_f32_e32 v54, v56, v92
	v_mul_f32_e32 v55, v58, v93
	v_mul_f32_e32 v56, v60, v94
	v_cvt_pk_bf16_f32 v50, v49, v50
	v_cvt_pk_bf16_f32 v51, v54, v51
	v_cvt_pk_bf16_f32 v52, v55, v52
	v_cvt_pk_bf16_f32 v53, v56, v53
	global_store_dwordx4 v[62:63], v[50:53], off
	v_mul_f32_e32 v49, v32, v72
	v_mul_f32_e32 v58, v33, v73
	v_mul_f32_e32 v59, v34, v74
	v_mul_f32_e32 v60, v35, v75
	v_mul_f32_e32 v61, v36, v76
	v_mul_f32_e32 v62, v37, v77
	v_mul_f32_e32 v63, v38, v78
	v_mul_f32_e32 v68, v39, v79
	ds_read_b128 v[32:35], v48 offset:18432
	ds_read_b128 v[36:39], v48 offset:18448
	v_mov_b64_e32 v[54:55], v[64:65]
	v_mov_b64_e32 v[56:57], v[66:67]
	s_waitcnt vmcnt(6)
	v_mov_b32_e32 v50, v222
	v_mov_b32_e32 v51, v223
	v_mov_b32_e32 v52, v224
	v_mov_b32_e32 v53, v225
	v_lshlrev_b32_e32 v69, 16, v50
	v_and_b32_e32 v50, 0xffff0000, v50
	v_lshlrev_b32_e32 v92, 16, v51
	v_and_b32_e32 v51, 0xffff0000, v51
	v_lshlrev_b32_e32 v93, 16, v52
	v_and_b32_e32 v52, 0xffff0000, v52
	v_lshlrev_b32_e32 v94, 16, v53
	v_and_b32_e32 v53, 0xffff0000, v53
	s_waitcnt lgkmcnt(1)
	v_mul_f32_e32 v32, v32, v69
	v_mul_f32_e32 v33, v33, v50
	v_mul_f32_e32 v34, v34, v92
	v_mul_f32_e32 v35, v35, v51
	s_waitcnt lgkmcnt(0)
; #define LAS __attribute__((address_space(3)))
; __device__ __forceinline__ unsigned cvt_pk_bf16(float lo, float hi) { unsigned r; asm volatile("v_cvt_pk_bf16_f32 %0, %1, %2" : "=v"(r) : "v"(lo), "v"(hi)); return r; }
; __device__ __forceinline__ float bf_lo(unsigned w) { return __uint_as_float(w << 16); }
; __device__ __forceinline__ float bf_hi(unsigned w) { return __uint_as_float(w & 0xffff0000u); }
; __device__ __forceinline__ int crow(int r, int hi) { return (r & 3) + 8 * (r >> 2) + 4 * hi; }
; __device__ __forceinline__ void fox_block(const BlockRef& cur, const BlockRef& nxt, char* lds, Seam& S, const int tid) {
;     ...
;     for (int d0 = 0; d0 < 4; ++d0) {
; #pragma unroll
;         for (int r = 0; r < 16; ++r) stg[crow(r, hi) * 32 + r32] = o[d0][r] * rli[r];
;         asm volatile("s_waitcnt lgkmcnt(0)" ::: "memory");
;         gbf16* op = obase; const gbf16* zp = zbase;
; #pragma unroll
;         for (int i = 0; i < 2; ++i) {
;             asm volatile("" : "+v"(op), "+v"(zp));
;             const f32x4 v0 = *(const LAS f32x4*)(stg + (er + 16 * i) * 32 + 8 * eq), v1 = *(const LAS f32x4*)(stg + (er + 16 * i) * 32 + 8 * eq + 4);
;             const u32x4 z = __builtin_nontemporal_load((const gu32x4*)(zp + d0 * 32));
;             u32x4 w; w.x = cvt_pk_bf16(v0.x * bf_lo(z.x), v0.y * bf_hi(z.x)); w.y = cvt_pk_bf16(v0.z * bf_lo(z.y), v0.w * bf_hi(z.y));
;             w.z = cvt_pk_bf16(v1.x * bf_lo(z.z), v1.y * bf_hi(z.z)); w.w = cvt_pk_bf16(v1.z * bf_lo(z.w), v1.w * bf_hi(z.w));
;             *(gu32x4*)(op + d0 * 32) = w;
;             op += 16 * LD; zp += 16 * LD; }
;         asm volatile("s_waitcnt lgkmcnt(0)" ::: "memory"); }
	v_mul_f32_e32 v36, v36, v93
	v_mul_f32_e32 v37, v37, v52
	v_mul_f32_e32 v38, v38, v94
	v_mul_f32_e32 v39, v39, v53
	v_cvt_pk_bf16_f32 v32, v32, v33
	v_cvt_pk_bf16_f32 v33, v34, v35
	v_cvt_pk_bf16_f32 v34, v36, v37
	v_cvt_pk_bf16_f32 v35, v38, v39
	global_store_dwordx4 v[70:71], v[32:35], off
	s_waitcnt lgkmcnt(0)
	ds_write2_b32 v88, v49, v58 offset1:32
	ds_write2_b32 v88, v59, v60 offset0:64 offset1:96
	ds_write2_b32 v89, v61, v62 offset1:32
	ds_write2_b32 v89, v63, v68 offset0:64 offset1:96
	ds_write2_b32 v90, v40, v41 offset1:32
	ds_write2_b32 v90, v42, v43 offset0:64 offset1:96
	ds_write2_b32 v91, v44, v45 offset1:32
	ds_write2_b32 v91, v46, v47 offset0:64 offset1:96
	s_waitcnt lgkmcnt(0)
	ds_read_b128 v[36:39], v48 offset:16384
	ds_read_b128 v[40:43], v48 offset:16400
	v_lshl_add_u64 v[44:45], v[54:55], 0, s[0:1]
	v_lshl_add_u64 v[46:47], v[56:57], 0, s[0:1]
	s_waitcnt vmcnt(6)
	v_mov_b32_e32 v32, v226
	v_mov_b32_e32 v33, v227
	v_mov_b32_e32 v34, v228
	v_mov_b32_e32 v35, v229
	v_lshlrev_b32_e32 v49, 16, v32
	v_and_b32_e32 v32, 0xffff0000, v32
	v_lshlrev_b32_e32 v50, 16, v33
	v_and_b32_e32 v33, 0xffff0000, v33
	v_lshlrev_b32_e32 v51, 16, v34
	v_and_b32_e32 v34, 0xffff0000, v34
	v_lshlrev_b32_e32 v52, 16, v35
	v_and_b32_e32 v35, 0xffff0000, v35
	s_waitcnt lgkmcnt(1)
	v_mul_f32_e32 v32, v37, v32
	v_mul_f32_e32 v33, v39, v33
	s_waitcnt lgkmcnt(0)
	v_mul_f32_e32 v34, v41, v34
	v_mul_f32_e32 v35, v43, v35
	v_mul_f32_e32 v36, v36, v49
	v_mul_f32_e32 v37, v38, v50
	v_mul_f32_e32 v38, v40, v51
	v_mul_f32_e32 v39, v42, v52
	v_cvt_pk_bf16_f32 v32, v36, v32
	v_cvt_pk_bf16_f32 v33, v37, v33
	v_cvt_pk_bf16_f32 v34, v38, v34
	v_cvt_pk_bf16_f32 v35, v39, v35
	global_store_dwordx4 v[54:55], v[32:35], off offset:64
	v_mul_f32_e32 v40, v16, v72
	v_mul_f32_e32 v41, v17, v73
	v_mul_f32_e32 v42, v18, v74
	v_mul_f32_e32 v43, v19, v75
	v_mul_f32_e32 v46, v20, v76
	v_mul_f32_e32 v47, v21, v77
	v_mul_f32_e32 v49, v22, v78
	v_mul_f32_e32 v50, v23, v79
	ds_read_b128 v[16:19], v48 offset:18432
	ds_read_b128 v[20:23], v48 offset:18448
	v_mov_b64_e32 v[36:37], v[64:65]
	v_mov_b64_e32 v[38:39], v[66:67]
	s_waitcnt vmcnt(6)
	v_mov_b32_e32 v32, v230
	v_mov_b32_e32 v33, v231
	v_mov_b32_e32 v34, v232
	v_mov_b32_e32 v35, v233
	v_lshlrev_b32_e32 v51, 16, v32
	v_and_b32_e32 v32, 0xffff0000, v32
	v_lshlrev_b32_e32 v52, 16, v33
	v_and_b32_e32 v33, 0xffff0000, v33
	v_lshlrev_b32_e32 v53, 16, v34
	v_and_b32_e32 v34, 0xffff0000, v34
	v_lshlrev_b32_e32 v54, 16, v35
	v_and_b32_e32 v35, 0xffff0000, v35
	s_waitcnt lgkmcnt(1)
	v_mul_f32_e32 v16, v16, v51
	v_mul_f32_e32 v17, v17, v32
	v_mul_f32_e32 v18, v18, v52
	v_mul_f32_e32 v19, v19, v33
	s_waitcnt lgkmcnt(0)
	v_mul_f32_e32 v20, v20, v53
	v_mul_f32_e32 v21, v21, v34
	v_mul_f32_e32 v22, v22, v54
	v_mul_f32_e32 v23, v23, v35
	v_cvt_pk_bf16_f32 v16, v16, v17
	v_cvt_pk_bf16_f32 v17, v18, v19
	v_cvt_pk_bf16_f32 v18, v20, v21
	v_cvt_pk_bf16_f32 v19, v22, v23
	global_store_dwordx4 v[44:45], v[16:19], off offset:64
	s_waitcnt lgkmcnt(0)
	ds_write2_b32 v88, v40, v41 offset1:32
	ds_write2_b32 v88, v42, v43 offset0:64 offset1:96
	ds_write2_b32 v89, v46, v47 offset1:32
	ds_write2_b32 v89, v49, v50 offset0:64 offset1:96
	ds_write2_b32 v90, v24, v25 offset1:32
	ds_write2_b32 v90, v26, v27 offset0:64 offset1:96
	ds_write2_b32 v91, v28, v29 offset1:32
	ds_write2_b32 v91, v30, v31 offset0:64 offset1:96
	s_waitcnt lgkmcnt(0)
	ds_read_b128 v[20:23], v48 offset:16384
	ds_read_b128 v[24:27], v48 offset:16400
	v_lshl_add_u64 v[28:29], v[36:37], 0, s[0:1]
	v_lshl_add_u64 v[30:31], v[38:39], 0, s[0:1]
	s_waitcnt vmcnt(6)
	v_mov_b32_e32 v16, v234
	v_mov_b32_e32 v17, v235
	v_mov_b32_e32 v18, v236
	v_mov_b32_e32 v19, v237
	v_lshlrev_b32_e32 v32, 16, v16
	v_and_b32_e32 v16, 0xffff0000, v16
	v_lshlrev_b32_e32 v33, 16, v17
	v_and_b32_e32 v17, 0xffff0000, v17
	v_lshlrev_b32_e32 v34, 16, v18
	v_and_b32_e32 v18, 0xffff0000, v18
	v_lshlrev_b32_e32 v35, 16, v19
	v_and_b32_e32 v19, 0xffff0000, v19
	s_waitcnt lgkmcnt(1)
; #define LAS __attribute__((address_space(3)))
; __device__ __forceinline__ unsigned cvt_pk_bf16(float lo, float hi) { unsigned r; asm volatile("v_cvt_pk_bf16_f32 %0, %1, %2" : "=v"(r) : "v"(lo), "v"(hi)); return r; }
; __device__ __forceinline__ float bf_lo(unsigned w) { return __uint_as_float(w << 16); }
; __device__ __forceinline__ float bf_hi(unsigned w) { return __uint_as_float(w & 0xffff0000u); }
; __device__ __forceinline__ int crow(int r, int hi) { return (r & 3) + 8 * (r >> 2) + 4 * hi; }
; #define WAITV_BAR(N) asm volatile("s_waitcnt vmcnt(" #N ") lgkmcnt(0)\n\ts_barrier" ::: "memory")
; __device__ __forceinline__ void fox_block(const BlockRef& cur, const BlockRef& nxt, char* lds, Seam& S, const int tid) {
;     ...
;     for (int d0 = 0; d0 < 4; ++d0) {
; #pragma unroll
;         for (int r = 0; r < 16; ++r) stg[crow(r, hi) * 32 + r32] = o[d0][r] * rli[r];
;         asm volatile("s_waitcnt lgkmcnt(0)" ::: "memory");
;         gbf16* op = obase; const gbf16* zp = zbase;
; #pragma unroll
;         for (int i = 0; i < 2; ++i) {
;             asm volatile("" : "+v"(op), "+v"(zp));
;             const f32x4 v0 = *(const LAS f32x4*)(stg + (er + 16 * i) * 32 + 8 * eq), v1 = *(const LAS f32x4*)(stg + (er + 16 * i) * 32 + 8 * eq + 4);
;             const u32x4 z = __builtin_nontemporal_load((const gu32x4*)(zp + d0 * 32));
;             u32x4 w; w.x = cvt_pk_bf16(v0.x * bf_lo(z.x), v0.y * bf_hi(z.x)); w.y = cvt_pk_bf16(v0.z * bf_lo(z.y), v0.w * bf_hi(z.y));
;             w.z = cvt_pk_bf16(v1.x * bf_lo(z.z), v1.y * bf_hi(z.z)); w.w = cvt_pk_bf16(v1.z * bf_lo(z.w), v1.w * bf_hi(z.w));
;             *(gu32x4*)(op + d0 * 32) = w;
;             op += 16 * LD; zp += 16 * LD; }
;         asm volatile("s_waitcnt lgkmcnt(0)" ::: "memory"); }
;     WAITV_BAR(0);
	v_mul_f32_e32 v16, v21, v16
	v_mul_f32_e32 v17, v23, v17
	s_waitcnt lgkmcnt(0)
	v_mul_f32_e32 v18, v25, v18
	v_mul_f32_e32 v19, v27, v19
	v_mul_f32_e32 v20, v20, v32
	v_mul_f32_e32 v21, v22, v33
	v_mul_f32_e32 v22, v24, v34
	v_mul_f32_e32 v23, v26, v35
	v_cvt_pk_bf16_f32 v16, v20, v16
	v_cvt_pk_bf16_f32 v17, v21, v17
	v_cvt_pk_bf16_f32 v18, v22, v18
	v_cvt_pk_bf16_f32 v19, v23, v19
	global_store_dwordx4 v[36:37], v[16:19], off offset:128
	v_mul_f32_e32 v20, v0, v72
	v_mul_f32_e32 v21, v1, v73
	v_mul_f32_e32 v22, v2, v74
	v_mul_f32_e32 v23, v3, v75
	v_mul_f32_e32 v24, v4, v76
	v_mul_f32_e32 v25, v5, v77
	v_mul_f32_e32 v26, v6, v78
	v_mul_f32_e32 v27, v7, v79
	ds_read_b128 v[0:3], v48 offset:18432
	ds_read_b128 v[4:7], v48 offset:18448
	s_waitcnt vmcnt(6)
	v_mov_b32_e32 v16, v238
	v_mov_b32_e32 v17, v239
	v_mov_b32_e32 v18, v240
	v_mov_b32_e32 v19, v241
	v_lshlrev_b32_e32 v30, 16, v16
	v_and_b32_e32 v16, 0xffff0000, v16
	v_lshlrev_b32_e32 v31, 16, v17
	v_and_b32_e32 v17, 0xffff0000, v17
	v_lshlrev_b32_e32 v32, 16, v18
	v_and_b32_e32 v18, 0xffff0000, v18
	v_lshlrev_b32_e32 v33, 16, v19
	v_and_b32_e32 v19, 0xffff0000, v19
	s_waitcnt lgkmcnt(1)
	v_mul_f32_e32 v0, v0, v30
	v_mul_f32_e32 v1, v1, v16
	v_mul_f32_e32 v2, v2, v31
	v_mul_f32_e32 v3, v3, v17
	s_waitcnt lgkmcnt(0)
	v_mul_f32_e32 v4, v4, v32
	v_mul_f32_e32 v5, v5, v18
	v_mul_f32_e32 v6, v6, v33
	v_mul_f32_e32 v7, v7, v19
	v_cvt_pk_bf16_f32 v0, v0, v1
	v_cvt_pk_bf16_f32 v1, v2, v3
	v_cvt_pk_bf16_f32 v2, v4, v5
	v_cvt_pk_bf16_f32 v3, v6, v7
	global_store_dwordx4 v[28:29], v[0:3], off offset:128
	s_waitcnt lgkmcnt(0)
	ds_write2_b32 v88, v20, v21 offset1:32
	ds_write2_b32 v88, v22, v23 offset0:64 offset1:96
	ds_write2_b32 v89, v24, v25 offset1:32
	ds_write2_b32 v89, v26, v27 offset0:64 offset1:96
	ds_write2_b32 v90, v8, v9 offset1:32
	ds_write2_b32 v90, v10, v11 offset0:64 offset1:96
	ds_write2_b32 v91, v12, v13 offset1:32
	ds_write2_b32 v91, v14, v15 offset0:64 offset1:96
	s_waitcnt lgkmcnt(0)
	ds_read_b128 v[4:7], v48 offset:16384
	ds_read_b128 v[8:11], v48 offset:16400
	v_lshl_add_u64 v[12:13], v[64:65], 0, s[0:1]
	v_lshl_add_u64 v[14:15], v[66:67], 0, s[0:1]
	v_readlane_b32 s0, v248, 61
	v_readlane_b32 s1, v248, 62
	s_add_i32 s0, s0, s1
	s_cmpk_lt_i32 s60, 0x100
	v_writelane_b32 v248, s0, 61
	s_waitcnt vmcnt(6)
	v_mov_b32_e32 v0, v242
	v_mov_b32_e32 v1, v243
	v_mov_b32_e32 v2, v244
	v_mov_b32_e32 v3, v245
	v_lshlrev_b32_e32 v16, 16, v0
	v_and_b32_e32 v0, 0xffff0000, v0
	v_lshlrev_b32_e32 v17, 16, v1
	v_and_b32_e32 v1, 0xffff0000, v1
	v_lshlrev_b32_e32 v18, 16, v2
	v_and_b32_e32 v2, 0xffff0000, v2
	v_lshlrev_b32_e32 v19, 16, v3
	v_and_b32_e32 v3, 0xffff0000, v3
	s_waitcnt lgkmcnt(1)
	v_mul_f32_e32 v0, v5, v0
	v_mul_f32_e32 v1, v7, v1
	s_waitcnt lgkmcnt(0)
	v_mul_f32_e32 v2, v9, v2
	v_mul_f32_e32 v3, v11, v3
	v_mul_f32_e32 v4, v4, v16
	v_mul_f32_e32 v5, v6, v17
	v_mul_f32_e32 v6, v8, v18
	v_mul_f32_e32 v7, v10, v19
	v_cvt_pk_bf16_f32 v0, v4, v0
	v_cvt_pk_bf16_f32 v1, v5, v1
	v_cvt_pk_bf16_f32 v2, v6, v2
	v_cvt_pk_bf16_f32 v3, v7, v3
	global_store_dwordx4 v[64:65], v[0:3], off offset:192
	global_load_dwordx4 v[0:3], v[14:15], off offset:192 nt
	ds_read_b128 v[4:7], v48 offset:18432
	ds_read_b128 v[8:11], v48 offset:18448
	s_waitcnt vmcnt(0)
	v_lshlrev_b32_e32 v14, 16, v0
	v_and_b32_e32 v0, 0xffff0000, v0
	v_lshlrev_b32_e32 v15, 16, v1
	v_and_b32_e32 v1, 0xffff0000, v1
	v_lshlrev_b32_e32 v16, 16, v2
	v_and_b32_e32 v2, 0xffff0000, v2
	v_lshlrev_b32_e32 v17, 16, v3
	v_and_b32_e32 v3, 0xffff0000, v3
	s_waitcnt lgkmcnt(1)
	v_mul_f32_e32 v0, v5, v0
	v_mul_f32_e32 v1, v7, v1
	s_waitcnt lgkmcnt(0)
	v_mul_f32_e32 v2, v9, v2
	v_mul_f32_e32 v3, v11, v3
	v_mul_f32_e32 v4, v4, v14
	v_mul_f32_e32 v5, v6, v15
	v_mul_f32_e32 v6, v8, v16
	v_mul_f32_e32 v7, v10, v17
	v_cvt_pk_bf16_f32 v0, v4, v0
	v_cvt_pk_bf16_f32 v1, v5, v1
	v_cvt_pk_bf16_f32 v2, v6, v2
	v_cvt_pk_bf16_f32 v3, v7, v3
	global_store_dwordx4 v[12:13], v[0:3], off offset:192
	s_waitcnt lgkmcnt(0)
	s_waitcnt vmcnt(0) lgkmcnt(0)
	s_barrier
	s_cbranch_scc0 .LBB0_590

; #define SBAR() __builtin_amdgcn_sched_barrier(0)
; #define PV_RD(d0, kh, X) do { constexpr int b_ = v_rd_off(d0, 2 * (kh), 0); TRRD(X##l0, b_); TRRD(X##h0, b_ + 2048); TRRD(X##l1, b_ + 4096); TRRD(X##h1, b_ + 6144); } while (0)
; #define PV_MM(d0, X, PA, PB) do { \
;         o[d0] = __builtin_amdgcn_mfma_f32_32x32x16_bf16(PA, (bf16x8){X##l0[0], X##l0[1], X##l0[2], X##l0[3], X##h0[0], X##h0[1], X##h0[2], X##h0[3]}, o[d0], 0, 0, 0);   \
;         o[d0] = __builtin_amdgcn_mfma_f32_32x32x16_bf16(PB, (bf16x8){X##l1[0], X##l1[1], X##l1[2], X##l1[3], X##h1[0], X##h1[1], X##h1[2], X##h1[3]}, o[d0], 0, 0, 0); } while (0)
; #define PV_W4() do { asm volatile("s_waitcnt lgkmcnt(4)" ::: "memory"); SBAR(); } while (0)
; #define PV_W0() do { asm volatile("s_waitcnt lgkmcnt(0)" ::: "memory"); SBAR(); } while (0)
; __device__ __forceinline__ void finishSM(f32x16& p0, f32x16& p1, float alpha, float& l_reg, bf16x8& pa0, bf16x8& pa1, bf16x8& pa2, bf16x8& pa3) {
; #pragma unroll
;     for (int r = 0; r < 16; ++r) p1[r] = __builtin_amdgcn_exp2f(p1[r]);
;     float ps = 0;
; #pragma unroll
;     for (int r = 0; r < 16; ++r) ps += p0[r];
; #pragma unroll
;     for (int r = 0; r < 16; ++r) ps += p1[r];
;     { auto rr = __builtin_amdgcn_permlane32_swap(__float_as_uint(ps), __float_as_uint(ps), false, false);
;       ps = __uint_as_float(rr[0]) + __uint_as_float(rr[1]); }
;     l_reg = l_reg * alpha + ps;
;     ...
;     PK4(p0, 0, pa0); PK4(p0, 8, pa1); PK4(p1, 0, pa2); PK4(p1, 8, pa3);
; __device__ __forceinline__ void pv_tile(f32x16* o, int vb0, bf16x8 pa0, bf16x8 pa1, bf16x8 pa2, bf16x8 pa3) {
;     ...
;     s16x4 al0, al1, ah0, ah1, bl0, bl1, bh0, bh1;
;     PV_RD(0, 0, a);
;     PV_RD(0, 1, b); PV_W4(); PV_MM(0, a, pa0, pa1); SBAR();
;     PV_RD(1, 0, a); PV_W4(); PV_MM(0, b, pa2, pa3); SBAR();
;     PV_RD(1, 1, b); PV_W4(); PV_MM(1, a, pa0, pa1); SBAR();
;     PV_RD(2, 0, a); PV_W4(); PV_MM(1, b, pa2, pa3); SBAR();
;     PV_RD(2, 1, b); PV_W4(); PV_MM(2, a, pa0, pa1); SBAR();
;     PV_RD(3, 0, a); PV_W4(); PV_MM(2, b, pa2, pa3); SBAR();
;     PV_RD(3, 1, b); PV_W4(); PV_MM(3, a, pa0, pa1); SBAR();
;     PV_W0(); PV_MM(3, b, pa2, pa3);
.LBB0_553:
	v_add_f32_e32 v64, 0, v221
	v_add_f32_e32 v64, v236, v64
	v_add_f32_e32 v64, v233, v64
	v_add_f32_e32 v64, v235, v64
	v_add_f32_e32 v64, v231, v64
	v_add_f32_e32 v64, v234, v64
	v_add_f32_e32 v64, v230, v64
	v_add_f32_e32 v64, v232, v64
	v_add_f32_e32 v64, v227, v64
	v_add_f32_e32 v64, v229, v64
	v_add_f32_e32 v64, v225, v64
	v_add_f32_e32 v64, v228, v64
	v_exp_f32_e32 v74, v168
	v_add_f32_e32 v64, v223, v64
	v_exp_f32_e32 v75, v169
	v_add_f32_e32 v64, v226, v64
	v_exp_f32_e32 v76, v172
	v_add_f32_e32 v64, v222, v64
	v_exp_f32_e32 v77, v173
	v_add_f32_e32 v64, v224, v64
	v_exp_f32_e32 v78, v176
	v_add_f32_e32 v64, v74, v64
	v_exp_f32_e32 v79, v177
	v_add_f32_e32 v64, v75, v64
	v_exp_f32_e32 v80, v166
	v_add_f32_e32 v64, v76, v64
	v_exp_f32_e32 v81, v167
	v_add_f32_e32 v64, v77, v64
	v_exp_f32_e32 v82, v170
	v_add_f32_e32 v64, v78, v64
	v_exp_f32_e32 v83, v171
	v_add_f32_e32 v64, v79, v64
	v_exp_f32_e32 v84, v174
	v_add_f32_e32 v64, v80, v64
	v_exp_f32_e32 v85, v175
	v_add_f32_e32 v64, v81, v64
	v_exp_f32_e32 v86, v178
	v_add_f32_e32 v64, v82, v64
	v_exp_f32_e32 v87, v179
	v_add_f32_e32 v64, v83, v64
	v_readlane_b32 s7, v247, 12
	v_readlane_b32 s2, v247, 13
	v_exp_f32_e32 v88, v164
	v_add_f32_e32 v64, v84, v64
	s_or_b32 s2, s7, s2
	v_exp_f32_e32 v89, v165
	v_add_f32_e32 v64, v85, v64
	s_ashr_i32 s3, s2, 31
	v_readlane_b32 s4, v248, 63
	v_add_f32_e32 v64, v86, v64
	s_lshl_b64 s[2:3], s[2:3], 11
	v_readlane_b32 s5, v247, 0
	v_add_f32_e32 v64, v87, v64
	s_or_b64 s[2:3], s[2:3], s[4:5]
	v_add_f32_e32 v64, v88, v64
	s_lshl_b64 s[68:69], s[2:3], 1
	v_readlane_b32 s93, v247, 10
	v_add_f32_e32 v64, v89, v64
	s_add_u32 s2, s93, s68
	v_readlane_b32 s3, v248, 37
	v_mov_b32_e32 v65, v64
	s_addc_u32 s3, s3, s69
	s_nop 0
	v_permlane32_swap_b32_e32 v64, v65
	v_cvt_pk_bf16_f32 v66, v221, v236
	v_cvt_pk_bf16_f32 v67, v233, v235
	v_cvt_pk_bf16_f32 v68, v231, v234
	v_cvt_pk_bf16_f32 v69, v230, v232
	v_cvt_pk_bf16_f32 v70, v227, v229
	v_cvt_pk_bf16_f32 v71, v225, v228
	v_cvt_pk_bf16_f32 v72, v223, v226
	v_cvt_pk_bf16_f32 v73, v222, v224
	v_cvt_pk_bf16_f32 v74, v74, v75
	v_cvt_pk_bf16_f32 v75, v76, v77
	v_cvt_pk_bf16_f32 v76, v78, v79
	v_cvt_pk_bf16_f32 v77, v80, v81
	v_cvt_pk_bf16_f32 v78, v82, v83
	v_cvt_pk_bf16_f32 v79, v84, v85
	v_cvt_pk_bf16_f32 v80, v86, v87
	v_cvt_pk_bf16_f32 v81, v88, v89
	s_nop 0
	v_permlane32_swap_b32_e32 v66, v68
	v_permlane32_swap_b32_e32 v67, v69
	v_permlane32_swap_b32_e32 v70, v72
	v_permlane32_swap_b32_e32 v71, v73
	v_permlane32_swap_b32_e32 v74, v76
	v_permlane32_swap_b32_e32 v75, v77
	v_permlane32_swap_b32_e32 v78, v80
	v_permlane32_swap_b32_e32 v79, v81
	v_add_u32_e32 v98, s76, v192
	ds_read_b64_tr_b16 v[82:83], v98 offset:0
	ds_read_b64_tr_b16 v[84:85], v98 offset:0x800
	ds_read_b64_tr_b16 v[86:87], v98 offset:0x1000
	ds_read_b64_tr_b16 v[88:89], v98 offset:0x1800
	ds_read_b64_tr_b16 v[90:91], v98 offset:0x2000
	ds_read_b64_tr_b16 v[92:93], v98 offset:0x2800
	ds_read_b64_tr_b16 v[94:95], v98 offset:0x3000
	ds_read_b64_tr_b16 v[96:97], v98 offset:0x3800
	s_waitcnt lgkmcnt(4)
	s_nop 0
	v_mfma_f32_32x32x16_bf16 v[48:63], v[66:69], v[82:85], v[48:63]
	v_mfma_f32_32x32x16_bf16 v[48:63], v[70:73], v[86:89], v[48:63]
	ds_read_b64_tr_b16 v[82:83], v98 offset:0x200
	ds_read_b64_tr_b16 v[84:85], v98 offset:0xa00
	ds_read_b64_tr_b16 v[86:87], v98 offset:0x1200
	ds_read_b64_tr_b16 v[88:89], v98 offset:0x1a00
	s_waitcnt lgkmcnt(4)
	v_mfma_f32_32x32x16_bf16 v[48:63], v[74:77], v[90:93], v[48:63]
	v_mfma_f32_32x32x16_bf16 v[48:63], v[78:81], v[94:97], v[48:63]
	ds_read_b64_tr_b16 v[90:91], v98 offset:0x2200
	ds_read_b64_tr_b16 v[92:93], v98 offset:0x2a00
	ds_read_b64_tr_b16 v[94:95], v98 offset:0x3200
	ds_read_b64_tr_b16 v[96:97], v98 offset:0x3a00
	s_waitcnt lgkmcnt(4)
	v_mfma_f32_32x32x16_bf16 v[32:47], v[66:69], v[82:85], v[32:47]
	v_mfma_f32_32x32x16_bf16 v[32:47], v[70:73], v[86:89], v[32:47]
	ds_read_b64_tr_b16 v[82:83], v98 offset:0x400
	ds_read_b64_tr_b16 v[84:85], v98 offset:0xc00
	ds_read_b64_tr_b16 v[86:87], v98 offset:0x1400
	ds_read_b64_tr_b16 v[88:89], v98 offset:0x1c00
	s_waitcnt lgkmcnt(4)
	v_mfma_f32_32x32x16_bf16 v[32:47], v[74:77], v[90:93], v[32:47]
	v_mfma_f32_32x32x16_bf16 v[32:47], v[78:81], v[94:97], v[32:47]
	ds_read_b64_tr_b16 v[90:91], v98 offset:0x2400
	ds_read_b64_tr_b16 v[92:93], v98 offset:0x2c00
	ds_read_b64_tr_b16 v[94:95], v98 offset:0x3400
	ds_read_b64_tr_b16 v[96:97], v98 offset:0x3c00
	s_waitcnt lgkmcnt(4)
	v_mfma_f32_32x32x16_bf16 v[16:31], v[66:69], v[82:85], v[16:31]
	v_mfma_f32_32x32x16_bf16 v[16:31], v[70:73], v[86:89], v[16:31]
	ds_read_b64_tr_b16 v[82:83], v98 offset:0x600
	ds_read_b64_tr_b16 v[84:85], v98 offset:0xe00
	ds_read_b64_tr_b16 v[86:87], v98 offset:0x1600
	ds_read_b64_tr_b16 v[88:89], v98 offset:0x1e00
	s_waitcnt lgkmcnt(4)
	v_mfma_f32_32x32x16_bf16 v[16:31], v[74:77], v[90:93], v[16:31]
	v_mfma_f32_32x32x16_bf16 v[16:31], v[78:81], v[94:97], v[16:31]
	ds_read_b64_tr_b16 v[90:91], v98 offset:0x2600
	ds_read_b64_tr_b16 v[92:93], v98 offset:0x2e00
	ds_read_b64_tr_b16 v[94:95], v98 offset:0x3600
	ds_read_b64_tr_b16 v[96:97], v98 offset:0x3e00
	s_waitcnt lgkmcnt(4)
	v_mfma_f32_32x32x16_bf16 v[0:15], v[66:69], v[82:85], v[0:15]
	v_mfma_f32_32x32x16_bf16 v[0:15], v[70:73], v[86:89], v[0:15]
	s_waitcnt lgkmcnt(0)
	v_mfma_f32_32x32x16_bf16 v[0:15], v[74:77], v[90:93], v[0:15]
	v_mfma_f32_32x32x16_bf16 v[0:15], v[78:81], v[94:97], v[0:15]
	v_lshl_add_u64 v[66:67], s[2:3], 0, v[132:133]
	v_mov_b32_e32 v147, v129
	s_waitcnt vmcnt(0) lgkmcnt(0)
	s_barrier
; #define LAS __attribute__((address_space(3)))
; __device__ __forceinline__ unsigned cvt_pk_bf16(float lo, float hi) { unsigned r; asm volatile("v_cvt_pk_bf16_f32 %0, %1, %2" : "=v"(r) : "v"(lo), "v"(hi)); return r; }
; __device__ __forceinline__ float bf_lo(unsigned w) { return __uint_as_float(w << 16); }
; __device__ __forceinline__ float bf_hi(unsigned w) { return __uint_as_float(w & 0xffff0000u); }
; __device__ __forceinline__ void fox_block(const BlockRef& cur, const BlockRef& nxt, char* lds, Seam& S, const int tid) {
;     ...
;     { const bf16_t* Kh = nxt.K; const bf16_t* Vh = nxt.V;
; #pragma unroll
;       for (int d0 = 0; d0 < 8; ++d0) S.qr[d0] = load8(nxt.Q + (size_t)(wid * QBLK + r32) * LD + d0 * 16 + hi * 8);
;       SBAR(); DMA_K(0, 0); DMA_K(1, SLOT); DMA_V(0, 0); SBAR(); }
;     if (hi == 0) li_l[r32] = l_reg; asm volatile("s_waitcnt lgkmcnt(0)" ::: "memory");
;     float rli[16];
; #pragma unroll
;     for (int r = 0; r < 16; ++r) rli[r] = __builtin_amdgcn_rcpf(li_l[crow(r, hi)]);
;     typedef __attribute__((address_space(1))) bf16_t gbf16; typedef __attribute__((address_space(1))) u32x4 gu32x4;
;     LAS float* stg = (LAS float*)(lds3 + SLOT + wid * 4096);
;     const int er = lane >> 2, eq = lane & 3;
;     gbf16* obase = (gbf16*)(cur.O + (size_t)(wid * QBLK + er) * LD + 8 * eq); const gbf16* zbase = (const gbf16*)(cur.Z + (size_t)(wid * QBLK + er) * LD + 8 * eq);
; #pragma unroll
;     for (int d0 = 0; d0 < 4; ++d0) {
; #pragma unroll
;         for (int r = 0; r < 16; ++r) stg[crow(r, hi) * 32 + r32] = o[d0][r] * rli[r];
;         asm volatile("s_waitcnt lgkmcnt(0)" ::: "memory");
;         gbf16* op = obase; const gbf16* zp = zbase;
; #pragma unroll
;         for (int i = 0; i < 2; ++i) {
;             asm volatile("" : "+v"(op), "+v"(zp));
;             const f32x4 v0 = *(const LAS f32x4*)(stg + (er + 16 * i) * 32 + 8 * eq), v1 = *(const LAS f32x4*)(stg + (er + 16 * i) * 32 + 8 * eq + 4);
;             const u32x4 z = __builtin_nontemporal_load((const gu32x4*)(zp + d0 * 32));
;             u32x4 w; w.x = cvt_pk_bf16(v0.x * bf_lo(z.x), v0.y * bf_hi(z.x)); w.y = cvt_pk_bf16(v0.z * bf_lo(z.y), v0.w * bf_hi(z.y));
;             w.z = cvt_pk_bf16(v1.x * bf_lo(z.z), v1.y * bf_hi(z.z)); w.w = cvt_pk_bf16(v1.z * bf_lo(z.w), v1.w * bf_hi(z.w));
;             *(gu32x4*)(op + d0 * 32) = w;
;             op += 16 * LD; zp += 16 * LD; }
	v_lshl_add_u64 v[66:67], v[66:67], 0, v[146:147]
	global_load_dwordx4 v[96:99], v[66:67], off
	global_load_dwordx4 v[100:103], v[66:67], off offset:32
	global_load_dwordx4 v[104:107], v[66:67], off offset:64
	global_load_dwordx4 v[108:111], v[66:67], off offset:96
	global_load_dwordx4 v[112:115], v[66:67], off offset:128
	global_load_dwordx4 v[116:119], v[66:67], off offset:160
	global_load_dwordx4 v[120:123], v[66:67], off offset:192
	global_load_dwordx4 v[124:127], v[66:67], off offset:224
	v_readlane_b32 s2, v247, 15
	s_mov_b32 m0, s2
	v_readlane_b32 s2, v247, 16
	global_load_lds_dwordx4 v[144:145], off
	s_mov_b32 m0, s2
	v_readlane_b32 s2, v247, 17
	global_load_lds_dwordx4 v[142:143], off
	s_mov_b32 m0, s2
	v_readlane_b32 s2, v247, 18
	global_load_lds_dwordx4 v[136:137], off
	s_mov_b32 m0, s2
	v_readlane_b32 s2, v247, 19
	global_load_lds_dwordx4 v[138:139], off
	s_mov_b32 m0, s70
	s_nop 0
	global_load_lds_dwordx4 v[140:141], off
	s_mov_b32 m0, s2
	s_nop 0
	global_load_lds_dwordx4 v[134:135], off
	s_and_saveexec_b64 s[2:3], s[0:1]
	v_add_f32_e32 v64, v64, v65
	v_fmac_f32_e32 v64, v215, v158
	ds_write_b32 v214, v64
	s_or_b64 exec, exec, s[2:3]
	s_waitcnt lgkmcnt(0)
	ds_read_b128 v[64:67], v131
	ds_read_b128 v[68:71], v131 offset:32
	v_readlane_b32 s2, v248, 42
	s_add_u32 s2, s2, s78
	v_readlane_b32 s3, v248, 43
	s_waitcnt lgkmcnt(0)
	v_rcp_f32_e32 v72, v64
	v_rcp_f32_e32 v73, v65
	v_rcp_f32_e32 v74, v66
	v_rcp_f32_e32 v75, v67
	v_rcp_f32_e32 v76, v68
	ds_read_b128 v[64:67], v131 offset:64
	v_rcp_f32_e32 v77, v69
	v_rcp_f32_e32 v78, v70
	v_rcp_f32_e32 v79, v71
	ds_read_b128 v[68:71], v131 offset:96
	s_addc_u32 s3, s3, s79
	v_readlane_b32 s4, v248, 54
	s_add_u32 s4, s4, s78
	v_readlane_b32 s5, v248, 56
	v_readlane_b32 s6, v247, 14
	s_addc_u32 s5, s5, s79
	s_lshl_b32 s6, s6, 12
	s_waitcnt lgkmcnt(0)
	v_rcp_f32_e32 v84, v68
	s_add_i32 s6, s6, 0
	v_lshlrev_b32_e32 v68, 3, v155
	v_lshlrev_b32_e32 v133, 2, v199
	v_lshlrev_b32_e32 v170, 9, v213
	v_and_b32_e32 v132, 24, v68
	v_add3_u32 v68, s6, v133, v170
	v_rcp_f32_e32 v80, v64
	v_rcp_f32_e32 v81, v65
	v_mul_f32_e32 v48, v48, v72
	v_mul_f32_e32 v49, v49, v73
	v_add_u32_e32 v86, 0x4000, v68
	v_rcp_f32_e32 v82, v66
	v_rcp_f32_e32 v83, v67
	ds_write2_b32 v86, v48, v49 offset1:32
	v_mul_f32_e32 v48, v50, v74
	v_mul_f32_e32 v49, v51, v75
	v_rcp_f32_e32 v85, v69
	ds_write2_b32 v86, v48, v49 offset0:64 offset1:96
	v_mul_f32_e32 v48, v52, v76
	v_mul_f32_e32 v49, v53, v77
	v_add_u32_e32 v87, 0x4400, v68
	v_rcp_f32_e32 v70, v70
	v_rcp_f32_e32 v71, v71
	v_or_b32_e32 v64, s77, v191
	ds_write2_b32 v87, v48, v49 offset1:32
	v_mul_f32_e32 v48, v54, v78
	v_mul_f32_e32 v49, v55, v79
	v_ashrrev_i32_e32 v65, 31, v64
	ds_write2_b32 v87, v48, v49 offset0:64 offset1:96
	v_mul_f32_e32 v48, v56, v80
	v_mul_f32_e32 v49, v57, v81
	v_add_u32_e32 v88, 0x4800, v68
	v_lshlrev_b64 v[66:67], 12, v[64:65]
	ds_write2_b32 v88, v48, v49 offset1:32
	v_mul_f32_e32 v48, v58, v82
	v_mul_f32_e32 v49, v59, v83
	v_lshl_add_u64 v[64:65], s[4:5], 0, v[66:67]
	v_lshlrev_b32_e32 v128, 1, v132
	v_lshl_add_u64 v[66:67], s[2:3], 0, v[66:67]
	ds_write2_b32 v88, v48, v49 offset0:64 offset1:96
	v_mul_f32_e32 v48, v60, v84
	v_mul_f32_e32 v49, v61, v85
	v_add_u32_e32 v89, 0x4c00, v68
	v_lshl_add_u64 v[64:65], v[64:65], 0, v[128:129]
	v_lshl_add_u64 v[66:67], v[66:67], 0, v[128:129]
	ds_write2_b32 v89, v48, v49 offset1:32
	v_mul_f32_e32 v48, v62, v70
	v_mul_f32_e32 v49, v63, v71
	ds_write2_b32 v89, v48, v49 offset0:64 offset1:96
	v_mov_b64_e32 v[62:63], v[64:65]
	v_mov_b64_e32 v[68:69], v[66:67]
	s_waitcnt lgkmcnt(0)
	global_load_dwordx4 v[50:53], v[68:69], off nt
	v_add_co_u32_e32 v250, vcc, 0x10000, v68
	s_nop 1
	v_addc_co_u32_e32 v251, vcc, 0, v69, vcc
	global_load_dwordx4 v[222:225], v[250:251], off nt
	global_load_dwordx4 v[226:229], v[68:69], off offset:64 nt
	global_load_dwordx4 v[230:233], v[250:251], off offset:64 nt
	global_load_dwordx4 v[234:237], v[68:69], off offset:128 nt
	global_load_dwordx4 v[238:241], v[250:251], off offset:128 nt
	global_load_dwordx4 v[242:245], v[68:69], off offset:192 nt
	v_lshlrev_b32_e32 v145, 7, v191
	v_lshlrev_b32_e32 v48, 2, v132
	v_add3_u32 v48, s6, v48, v145
	ds_read_b128 v[54:57], v48 offset:16384
	ds_read_b128 v[58:61], v48 offset:16400
	s_mov_b64 s[2:3], 0x10000
	v_mul_f32_e32 v40, v40, v80
	v_mul_f32_e32 v41, v41, v81
	v_mul_f32_e32 v42, v42, v82
	v_mul_f32_e32 v43, v43, v83
	v_mul_f32_e32 v44, v44, v84
	v_mul_f32_e32 v45, v45, v85
	v_mul_f32_e32 v46, v46, v70
	v_mul_f32_e32 v47, v47, v71
	v_mul_f32_e32 v24, v24, v80
	v_mul_f32_e32 v25, v25, v81
	v_mul_f32_e32 v26, v26, v82
	v_mul_f32_e32 v27, v27, v83
	v_mul_f32_e32 v28, v28, v84
	v_mul_f32_e32 v29, v29, v85
	v_mul_f32_e32 v30, v30, v70
	v_mul_f32_e32 v31, v31, v71
	v_mul_f32_e32 v8, v8, v80
	v_mul_f32_e32 v9, v9, v81
	v_mul_f32_e32 v10, v10, v82
	v_mul_f32_e32 v11, v11, v83
	v_mul_f32_e32 v12, v12, v84
	v_mul_f32_e32 v13, v13, v85
	v_mul_f32_e32 v14, v14, v70
	v_mul_f32_e32 v15, v15, v71
	s_movk_i32 s6, 0x60
	s_or_b32 s4, s7, 64
	s_mov_b32 s87, 4
	s_lshr_b32 s89, s4, 6
	s_waitcnt vmcnt(6)
	v_lshlrev_b32_e32 v49, 16, v50
	v_and_b32_e32 v50, 0xffff0000, v50
	v_lshlrev_b32_e32 v90, 16, v51
	v_and_b32_e32 v51, 0xffff0000, v51
	v_lshlrev_b32_e32 v91, 16, v52
	v_and_b32_e32 v52, 0xffff0000, v52
	s_waitcnt lgkmcnt(1)
	v_mul_f32_e32 v50, v55, v50
	v_mul_f32_e32 v51, v57, v51
	v_lshlrev_b32_e32 v92, 16, v53
	v_and_b32_e32 v53, 0xffff0000, v53
	v_mul_f32_e32 v49, v54, v49
	v_mul_f32_e32 v54, v56, v90
	s_waitcnt lgkmcnt(0)
; #define LAS __attribute__((address_space(3)))
; __device__ __forceinline__ unsigned cvt_pk_bf16(float lo, float hi) { unsigned r; asm volatile("v_cvt_pk_bf16_f32 %0, %1, %2" : "=v"(r) : "v"(lo), "v"(hi)); return r; }
; __device__ __forceinline__ float bf_lo(unsigned w) { return __uint_as_float(w << 16); }
; __device__ __forceinline__ float bf_hi(unsigned w) { return __uint_as_float(w & 0xffff0000u); }
; __device__ __forceinline__ int crow(int r, int hi) { return (r & 3) + 8 * (r >> 2) + 4 * hi; }
; __device__ __forceinline__ void fox_block(const BlockRef& cur, const BlockRef& nxt, char* lds, Seam& S, const int tid) {
;     ...
;     for (int d0 = 0; d0 < 4; ++d0) {
; #pragma unroll
;         for (int r = 0; r < 16; ++r) stg[crow(r, hi) * 32 + r32] = o[d0][r] * rli[r];
;         asm volatile("s_waitcnt lgkmcnt(0)" ::: "memory");
;         gbf16* op = obase; const gbf16* zp = zbase;
; #pragma unroll
;         for (int i = 0; i < 2; ++i) {
;             asm volatile("" : "+v"(op), "+v"(zp));
;             const f32x4 v0 = *(const LAS f32x4*)(stg + (er + 16 * i) * 32 + 8 * eq), v1 = *(const LAS f32x4*)(stg + (er + 16 * i) * 32 + 8 * eq + 4);
;             const u32x4 z = __builtin_nontemporal_load((const gu32x4*)(zp + d0 * 32));
;             u32x4 w; w.x = cvt_pk_bf16(v0.x * bf_lo(z.x), v0.y * bf_hi(z.x)); w.y = cvt_pk_bf16(v0.z * bf_lo(z.y), v0.w * bf_hi(z.y));
;             w.z = cvt_pk_bf16(v1.x * bf_lo(z.z), v1.y * bf_hi(z.z)); w.w = cvt_pk_bf16(v1.z * bf_lo(z.w), v1.w * bf_hi(z.w));
;             *(gu32x4*)(op + d0 * 32) = w;
;             op += 16 * LD; zp += 16 * LD; }
;         asm volatile("s_waitcnt lgkmcnt(0)" ::: "memory"); }
	v_mul_f32_e32 v55, v58, v91
	v_mul_f32_e32 v52, v59, v52
	v_cvt_pk_bf16_f32 v50, v49, v50
	v_cvt_pk_bf16_f32 v51, v54, v51
	v_mul_f32_e32 v56, v60, v92
	v_cvt_pk_bf16_f32 v52, v55, v52
	v_mul_f32_e32 v49, v61, v53
	v_cvt_pk_bf16_f32 v53, v56, v49
	global_store_dwordx4 v[62:63], v[50:53], off
	v_lshl_add_u64 v[54:55], v[62:63], 0, s[2:3]
	v_mul_f32_e32 v49, v32, v72
	v_lshl_add_u64 v[50:51], v[68:69], 0, s[2:3]
	v_mul_f32_e32 v60, v33, v73
	v_mul_f32_e32 v61, v34, v74
	v_mul_f32_e32 v62, v35, v75
	v_mul_f32_e32 v63, v36, v76
	v_mul_f32_e32 v68, v37, v77
	v_mul_f32_e32 v69, v38, v78
	v_mul_f32_e32 v90, v39, v79
	ds_read_b128 v[32:35], v48 offset:18432
	ds_read_b128 v[36:39], v48 offset:18448
	v_mov_b64_e32 v[56:57], v[66:67]
	v_mov_b64_e32 v[58:59], v[64:65]
	s_waitcnt vmcnt(6)
	v_mov_b32_e32 v50, v222
	v_mov_b32_e32 v51, v223
	v_mov_b32_e32 v52, v224
	v_mov_b32_e32 v53, v225
	v_lshlrev_b32_e32 v91, 16, v50
	v_and_b32_e32 v50, 0xffff0000, v50
	v_lshlrev_b32_e32 v92, 16, v51
	v_and_b32_e32 v51, 0xffff0000, v51
	v_lshlrev_b32_e32 v93, 16, v52
	v_and_b32_e32 v52, 0xffff0000, v52
	v_lshlrev_b32_e32 v94, 16, v53
	v_and_b32_e32 v53, 0xffff0000, v53
	s_waitcnt lgkmcnt(1)
	v_mul_f32_e32 v32, v32, v91
	v_mul_f32_e32 v33, v33, v50
	v_mul_f32_e32 v34, v34, v92
	v_mul_f32_e32 v35, v35, v51
	s_waitcnt lgkmcnt(0)
	v_mul_f32_e32 v36, v36, v93
	v_mul_f32_e32 v37, v37, v52
	v_mul_f32_e32 v38, v38, v94
	v_mul_f32_e32 v39, v39, v53
	v_cvt_pk_bf16_f32 v32, v32, v33
	v_cvt_pk_bf16_f32 v33, v34, v35
	v_cvt_pk_bf16_f32 v34, v36, v37
	v_cvt_pk_bf16_f32 v35, v38, v39
	global_store_dwordx4 v[54:55], v[32:35], off
	s_waitcnt lgkmcnt(0)
	ds_write2_b32 v86, v49, v60 offset1:32
	ds_write2_b32 v86, v61, v62 offset0:64 offset1:96
	ds_write2_b32 v87, v63, v68 offset1:32
	ds_write2_b32 v87, v69, v90 offset0:64 offset1:96
	ds_write2_b32 v88, v40, v41 offset1:32
	ds_write2_b32 v88, v42, v43 offset0:64 offset1:96
	ds_write2_b32 v89, v44, v45 offset1:32
	ds_write2_b32 v89, v46, v47 offset0:64 offset1:96
	s_waitcnt lgkmcnt(0)
	ds_read_b128 v[36:39], v48 offset:16384
	ds_read_b128 v[40:43], v48 offset:16400
	v_lshl_add_u64 v[44:45], v[58:59], 0, s[2:3]
	v_lshl_add_u64 v[46:47], v[56:57], 0, s[2:3]
	s_waitcnt vmcnt(6)
	v_mov_b32_e32 v32, v226
	v_mov_b32_e32 v33, v227
	v_mov_b32_e32 v34, v228
	v_mov_b32_e32 v35, v229
	v_lshlrev_b32_e32 v49, 16, v32
	v_and_b32_e32 v32, 0xffff0000, v32
	v_lshlrev_b32_e32 v50, 16, v33
	v_and_b32_e32 v33, 0xffff0000, v33
	v_lshlrev_b32_e32 v51, 16, v34
	v_and_b32_e32 v34, 0xffff0000, v34
	v_lshlrev_b32_e32 v52, 16, v35
	v_and_b32_e32 v35, 0xffff0000, v35
	s_waitcnt lgkmcnt(1)
	v_mul_f32_e32 v32, v37, v32
	v_mul_f32_e32 v33, v39, v33
	s_waitcnt lgkmcnt(0)
	v_mul_f32_e32 v34, v41, v34
	v_mul_f32_e32 v35, v43, v35
	v_mul_f32_e32 v36, v36, v49
	v_mul_f32_e32 v37, v38, v50
	v_mul_f32_e32 v38, v40, v51
	v_mul_f32_e32 v39, v42, v52
	v_cvt_pk_bf16_f32 v32, v36, v32
	v_cvt_pk_bf16_f32 v33, v37, v33
	v_cvt_pk_bf16_f32 v34, v38, v34
	v_cvt_pk_bf16_f32 v35, v39, v35
	global_store_dwordx4 v[58:59], v[32:35], off offset:64
	v_mul_f32_e32 v40, v16, v72
	v_mul_f32_e32 v41, v17, v73
	v_mul_f32_e32 v42, v18, v74
	v_mul_f32_e32 v43, v19, v75
	v_mul_f32_e32 v46, v20, v76
	v_mul_f32_e32 v47, v21, v77
	v_mul_f32_e32 v49, v22, v78
	v_mul_f32_e32 v50, v23, v79
	ds_read_b128 v[16:19], v48 offset:18432
	ds_read_b128 v[20:23], v48 offset:18448
	v_mov_b64_e32 v[36:37], v[66:67]
	v_mov_b64_e32 v[38:39], v[64:65]
	s_waitcnt vmcnt(6)
	v_mov_b32_e32 v32, v230
	v_mov_b32_e32 v33, v231
	v_mov_b32_e32 v34, v232
	v_mov_b32_e32 v35, v233
	v_lshlrev_b32_e32 v51, 16, v32
	v_and_b32_e32 v32, 0xffff0000, v32
	v_lshlrev_b32_e32 v52, 16, v33
	v_and_b32_e32 v33, 0xffff0000, v33
	v_lshlrev_b32_e32 v53, 16, v34
	v_and_b32_e32 v34, 0xffff0000, v34
	v_lshlrev_b32_e32 v54, 16, v35
	v_and_b32_e32 v35, 0xffff0000, v35
	s_waitcnt lgkmcnt(1)
	v_mul_f32_e32 v16, v16, v51
	v_mul_f32_e32 v17, v17, v32
	v_mul_f32_e32 v18, v18, v52
	v_mul_f32_e32 v19, v19, v33
	s_waitcnt lgkmcnt(0)
	v_mul_f32_e32 v20, v20, v53
	v_mul_f32_e32 v21, v21, v34
	v_mul_f32_e32 v22, v22, v54
	v_mul_f32_e32 v23, v23, v35
	v_cvt_pk_bf16_f32 v16, v16, v17
	v_cvt_pk_bf16_f32 v17, v18, v19
	v_cvt_pk_bf16_f32 v18, v20, v21
	v_cvt_pk_bf16_f32 v19, v22, v23
	global_store_dwordx4 v[44:45], v[16:19], off offset:64
	s_waitcnt lgkmcnt(0)
	ds_write2_b32 v86, v40, v41 offset1:32
	ds_write2_b32 v86, v42, v43 offset0:64 offset1:96
	ds_write2_b32 v87, v46, v47 offset1:32
	ds_write2_b32 v87, v49, v50 offset0:64 offset1:96
	ds_write2_b32 v88, v24, v25 offset1:32
	ds_write2_b32 v88, v26, v27 offset0:64 offset1:96
	ds_write2_b32 v89, v28, v29 offset1:32
	ds_write2_b32 v89, v30, v31 offset0:64 offset1:96
	s_waitcnt lgkmcnt(0)
	ds_read_b128 v[20:23], v48 offset:16384
	ds_read_b128 v[24:27], v48 offset:16400
	v_lshl_add_u64 v[28:29], v[38:39], 0, s[2:3]
	v_lshl_add_u64 v[30:31], v[36:37], 0, s[2:3]
	s_waitcnt vmcnt(6)
	v_mov_b32_e32 v16, v234
	v_mov_b32_e32 v17, v235
	v_mov_b32_e32 v18, v236
	v_mov_b32_e32 v19, v237
	v_lshlrev_b32_e32 v32, 16, v16
	v_and_b32_e32 v16, 0xffff0000, v16
	v_lshlrev_b32_e32 v33, 16, v17
	v_and_b32_e32 v17, 0xffff0000, v17
	v_lshlrev_b32_e32 v34, 16, v18
	v_and_b32_e32 v18, 0xffff0000, v18
	v_lshlrev_b32_e32 v35, 16, v19
	v_and_b32_e32 v19, 0xffff0000, v19
	s_waitcnt lgkmcnt(1)
	v_mul_f32_e32 v16, v21, v16
	v_mul_f32_e32 v17, v23, v17
	s_waitcnt lgkmcnt(0)
; #define LAS __attribute__((address_space(3)))
; __device__ __forceinline__ unsigned cvt_pk_bf16(float lo, float hi) { unsigned r; asm volatile("v_cvt_pk_bf16_f32 %0, %1, %2" : "=v"(r) : "v"(lo), "v"(hi)); return r; }
; __device__ __forceinline__ float bf_lo(unsigned w) { return __uint_as_float(w << 16); }
; __device__ __forceinline__ float bf_hi(unsigned w) { return __uint_as_float(w & 0xffff0000u); }
; __device__ __forceinline__ int crow(int r, int hi) { return (r & 3) + 8 * (r >> 2) + 4 * hi; }
; #define WAITV_BAR(N) asm volatile("s_waitcnt vmcnt(" #N ") lgkmcnt(0)\n\ts_barrier" ::: "memory")
; __device__ __forceinline__ void fox_block(const BlockRef& cur, const BlockRef& nxt, char* lds, Seam& S, const int tid) {
;     ...
;     for (int d0 = 0; d0 < 4; ++d0) {
; #pragma unroll
;         for (int r = 0; r < 16; ++r) stg[crow(r, hi) * 32 + r32] = o[d0][r] * rli[r];
;         asm volatile("s_waitcnt lgkmcnt(0)" ::: "memory");
;         gbf16* op = obase; const gbf16* zp = zbase;
; #pragma unroll
;         for (int i = 0; i < 2; ++i) {
;             asm volatile("" : "+v"(op), "+v"(zp));
;             const f32x4 v0 = *(const LAS f32x4*)(stg + (er + 16 * i) * 32 + 8 * eq), v1 = *(const LAS f32x4*)(stg + (er + 16 * i) * 32 + 8 * eq + 4);
;             const u32x4 z = __builtin_nontemporal_load((const gu32x4*)(zp + d0 * 32));
;             u32x4 w; w.x = cvt_pk_bf16(v0.x * bf_lo(z.x), v0.y * bf_hi(z.x)); w.y = cvt_pk_bf16(v0.z * bf_lo(z.y), v0.w * bf_hi(z.y));
;             w.z = cvt_pk_bf16(v1.x * bf_lo(z.z), v1.y * bf_hi(z.z)); w.w = cvt_pk_bf16(v1.z * bf_lo(z.w), v1.w * bf_hi(z.w));
;             *(gu32x4*)(op + d0 * 32) = w;
;             op += 16 * LD; zp += 16 * LD; }
;         asm volatile("s_waitcnt lgkmcnt(0)" ::: "memory"); }
;     WAITV_BAR(0);
	v_mul_f32_e32 v18, v25, v18
	v_mul_f32_e32 v19, v27, v19
	v_mul_f32_e32 v20, v20, v32
	v_mul_f32_e32 v21, v22, v33
	v_mul_f32_e32 v22, v24, v34
	v_mul_f32_e32 v23, v26, v35
	v_cvt_pk_bf16_f32 v16, v20, v16
	v_cvt_pk_bf16_f32 v17, v21, v17
	v_cvt_pk_bf16_f32 v18, v22, v18
	v_cvt_pk_bf16_f32 v19, v23, v19
	global_store_dwordx4 v[38:39], v[16:19], off offset:128
	v_mul_f32_e32 v20, v0, v72
	v_mul_f32_e32 v21, v1, v73
	v_mul_f32_e32 v22, v2, v74
	v_mul_f32_e32 v23, v3, v75
	v_mul_f32_e32 v24, v4, v76
	v_mul_f32_e32 v25, v5, v77
	v_mul_f32_e32 v26, v6, v78
	v_mul_f32_e32 v27, v7, v79
	ds_read_b128 v[0:3], v48 offset:18432
	ds_read_b128 v[4:7], v48 offset:18448
	s_waitcnt vmcnt(6)
	v_mov_b32_e32 v16, v238
	v_mov_b32_e32 v17, v239
	v_mov_b32_e32 v18, v240
	v_mov_b32_e32 v19, v241
	v_lshlrev_b32_e32 v30, 16, v16
	v_and_b32_e32 v16, 0xffff0000, v16
	v_lshlrev_b32_e32 v31, 16, v17
	v_and_b32_e32 v17, 0xffff0000, v17
	v_lshlrev_b32_e32 v32, 16, v18
	v_and_b32_e32 v18, 0xffff0000, v18
	v_lshlrev_b32_e32 v33, 16, v19
	v_and_b32_e32 v19, 0xffff0000, v19
	s_waitcnt lgkmcnt(1)
	v_mul_f32_e32 v0, v0, v30
	v_mul_f32_e32 v1, v1, v16
	v_mul_f32_e32 v2, v2, v31
	v_mul_f32_e32 v3, v3, v17
	s_waitcnt lgkmcnt(0)
	v_mul_f32_e32 v4, v4, v32
	v_mul_f32_e32 v5, v5, v18
	v_mul_f32_e32 v6, v6, v33
	v_mul_f32_e32 v7, v7, v19
	v_cvt_pk_bf16_f32 v0, v0, v1
	v_cvt_pk_bf16_f32 v1, v2, v3
	v_cvt_pk_bf16_f32 v2, v4, v5
	v_cvt_pk_bf16_f32 v3, v6, v7
	global_store_dwordx4 v[28:29], v[0:3], off offset:128
	s_waitcnt lgkmcnt(0)
	ds_write2_b32 v86, v20, v21 offset1:32
	ds_write2_b32 v86, v22, v23 offset0:64 offset1:96
	ds_write2_b32 v87, v24, v25 offset1:32
	ds_write2_b32 v87, v26, v27 offset0:64 offset1:96
	ds_write2_b32 v88, v8, v9 offset1:32
	ds_write2_b32 v88, v10, v11 offset0:64 offset1:96
	ds_write2_b32 v89, v12, v13 offset1:32
	ds_write2_b32 v89, v14, v15 offset0:64 offset1:96
	s_waitcnt lgkmcnt(0)
	ds_read_b128 v[4:7], v48 offset:16384
	ds_read_b128 v[8:11], v48 offset:16400
	v_lshl_add_u64 v[12:13], v[64:65], 0, s[2:3]
	v_lshl_add_u64 v[14:15], v[66:67], 0, s[2:3]
	v_readfirstlane_b32 s3, v155
	s_ashr_i32 s70, s3, 6
	s_lshl_b32 s5, s70, 7
	s_and_b32 s3, s3, 0x3fffffc0
	v_readlane_b32 s2, v248, 61
	s_lshl_b32 s3, s3, 2
	s_and_b32 s2, s2, 0x700
	s_lshl_b32 s71, s70, 5
	s_add_i32 s3, s3, 0
	s_add_i32 s3, s3, 0x18000
	s_waitcnt vmcnt(6)
	v_mov_b32_e32 v0, v242
	v_mov_b32_e32 v1, v243
	v_mov_b32_e32 v2, v244
	v_mov_b32_e32 v3, v245
	v_lshlrev_b32_e32 v16, 16, v0
	v_and_b32_e32 v0, 0xffff0000, v0
	v_lshlrev_b32_e32 v17, 16, v1
	v_and_b32_e32 v1, 0xffff0000, v1
	v_lshlrev_b32_e32 v18, 16, v2
	v_and_b32_e32 v2, 0xffff0000, v2
	v_lshlrev_b32_e32 v19, 16, v3
	v_and_b32_e32 v3, 0xffff0000, v3
	s_waitcnt lgkmcnt(1)
	v_mul_f32_e32 v0, v5, v0
	v_mul_f32_e32 v1, v7, v1
	s_waitcnt lgkmcnt(0)
	v_mul_f32_e32 v2, v9, v2
	v_mul_f32_e32 v3, v11, v3
	v_mul_f32_e32 v4, v4, v16
	v_mul_f32_e32 v5, v6, v17
	v_mul_f32_e32 v6, v8, v18
	v_mul_f32_e32 v7, v10, v19
	v_cvt_pk_bf16_f32 v0, v4, v0
	v_cvt_pk_bf16_f32 v1, v5, v1
	v_cvt_pk_bf16_f32 v2, v6, v2
	v_cvt_pk_bf16_f32 v3, v7, v3
	global_store_dwordx4 v[64:65], v[0:3], off offset:192
	global_load_dwordx4 v[0:3], v[14:15], off offset:192 nt
	v_or_b32_e32 v4, s5, v198
	s_ashr_i32 s5, s5, 4
	v_bitop3_b32 v36, s5, -13, v191 bitop3:0xc8
	s_lshr_b32 s5, s5, 1
	v_ashrrev_i32_e32 v5, 4, v4
	s_and_b32 s5, s5, 4
	v_or_b32_e32 v14, 64, v4
	v_bitop3_b32 v4, v5, v203, 3 bitop3:0x6c
	v_lshlrev_b32_e32 v5, 8, v5
	v_or3_b32 v6, v36, s5, v200
	v_lshl_or_b32 v128, v4, 4, v5
	v_lshlrev_b32_e32 v17, 8, v6
	ds_read_b128 v[4:7], v48 offset:18432
	ds_read_b128 v[8:11], v48 offset:18448
	v_ashrrev_i32_e32 v15, 4, v14
	v_bitop3_b32 v16, v15, v203, 7 bitop3:0x6c
	v_or_b32_e32 v134, v17, v204
	s_waitcnt vmcnt(0)
	v_lshlrev_b32_e32 v18, 16, v0
	v_and_b32_e32 v0, 0xffff0000, v0
	v_lshlrev_b32_e32 v19, 16, v1
	v_and_b32_e32 v1, 0xffff0000, v1
	v_lshlrev_b32_e32 v20, 16, v2
	v_and_b32_e32 v2, 0xffff0000, v2
	v_lshlrev_b32_e32 v21, 16, v3
	v_and_b32_e32 v3, 0xffff0000, v3
	s_waitcnt lgkmcnt(1)
	v_mul_f32_e32 v0, v5, v0
	v_mul_f32_e32 v1, v7, v1
	s_waitcnt lgkmcnt(0)
	v_mul_f32_e32 v2, v9, v2
	v_mul_f32_e32 v3, v11, v3
	v_mul_f32_e32 v4, v4, v18
	v_mul_f32_e32 v5, v6, v19
	v_mul_f32_e32 v6, v8, v20
	v_mul_f32_e32 v7, v10, v21
	v_cvt_pk_bf16_f32 v0, v4, v0
	v_cvt_pk_bf16_f32 v1, v5, v1
	v_cvt_pk_bf16_f32 v2, v6, v2
	v_cvt_pk_bf16_f32 v3, v7, v3
	global_store_dwordx4 v[12:13], v[0:3], off offset:192
	s_waitcnt lgkmcnt(0)
	s_waitcnt vmcnt(0) lgkmcnt(0)
	s_barrier
; #define LAS __attribute__((address_space(3)))
; __device__ __forceinline__ void partialSM(f32x16& p0, f32x16& p1, float& m_reg, float& mn, float& alpha) {
;     float pmax = p0[0];
; #pragma unroll
;     for (int r = 1; r < 16; ++r) pmax = fmaxf(pmax, p0[r]);
; #pragma unroll
;     for (int r = 0; r < 16; ++r) pmax = fmaxf(pmax, p1[r]);
;     { auto rr = __builtin_amdgcn_permlane32_swap(__float_as_uint(pmax), __float_as_uint(pmax), false, false);
;       pmax = fmaxf(__uint_as_float(rr[0]), __uint_as_float(rr[1])); }
;     if (__builtin_expect(__all((pmax - m_reg) <= THR2), 1)) { mn = m_reg; alpha = 1.f; }
;     else { mn = fmaxf(m_reg, pmax); alpha = __builtin_amdgcn_exp2f(m_reg - mn); m_reg = mn; }
; #pragma unroll
;     for (int r = 0; r < 16; ++r) p0[r] = p0[r] - mn;
; #pragma unroll
;     for (int r = 0; r < 16; ++r) p1[r] = p1[r] - mn;
; #pragma unroll
;     for (int r = 0; r < 16; ++r) p0[r] = __builtin_amdgcn_exp2f(p0[r]);
; }
; __device__ __forceinline__ void qkt(f32x16& p0, f32x16& p1, const char* Kslot, int r32, int hi, const bf16x8* qr, const LAS f32x4* cp) {
; #pragma unroll
;     for (int g = 0; g < 4; ++g) { const f32x4 c0 = cp[2 * g], c1 = cp[8 + 2 * g];
; #pragma unroll
;         for (int j = 0; j < 4; ++j) { p0[4 * g + j] = c0[j]; p1[4 * g + j] = c1[j]; } }
;     const char* kb[4];
; #pragma unroll
;     for (int dd = 0; dd < 4; ++dd) kb[dd] = Kslot + KSWZ(r32, (dd * 16 + hi * 8) * 2);
; #pragma unroll
;     for (int d0 = 0; d0 < 8; ++d0) { const char* a = kb[d0 & 3] + (d0 >> 2) * 128;
;         bf16x8 b0 = *reinterpret_cast<const bf16x8*>(a);
;         bf16x8 b1 = *reinterpret_cast<const bf16x8*>(a + 32 * 256);
;         p0 = __builtin_amdgcn_mfma_f32_32x32x16_bf16(b0, qr[d0], p0, 0, 0, 0);
;         p1 = __builtin_amdgcn_mfma_f32_32x32x16_bf16(b1, qr[d0], p1, 0, 0, 0); }
; }
	s_nop 1
	v_lshlrev_b32_e32 v0, 8, v15
	v_lshl_or_b32 v138, v16, 4, v0
	v_and_or_b32 v0, v14, s6, v202
	v_lshl_or_b32 v136, v0, 1, v17
	s_lshl_b32 s6, s70, 11
	s_add_i32 s86, s6, 0
	s_add_i32 m0, s86, 0x14000
	v_readlane_b32 s6, v247, 24
	global_load_lds_dwordx4 v128, s[66:67]
	s_add_i32 m0, s86, 0x14400
	v_readlane_b32 s7, v247, 25
	global_load_lds_dwordx4 v138, s[66:67]
	s_add_i32 m0, s86, 0x4000
	v_mov_b32_e32 v139, v129
	s_add_i32 s88, s71, s4
	s_nop 0
	global_load_lds_dwordx4 v134, s[6:7]
	s_add_i32 m0, s86, 0x4400
	s_movk_i32 s73, 0x4000
	global_load_lds_dwordx4 v136, s[6:7]
	v_mov_b32_e32 v135, v129
	v_mov_b32_e32 v137, v129
	s_add_i32 s89, s89, 4
	ds_read_b128 v[16:19], v209 offset:57344
	ds_read_b128 v[0:3], v205 offset:128
	ds_read_b128 v[4:7], v205 offset:160
	ds_read_b128 v[8:11], v205 offset:192
	ds_read_b128 v[12:15], v205 offset:224
	ds_read_b128 v[20:23], v209 offset:57472
	s_mov_b32 s4, 0xff800000
	s_waitcnt lgkmcnt(0)
	v_mfma_f32_32x32x16_bf16 v[0:15], v[16:19], v[96:99], v[0:15]
	ds_read_b128 v[16:19], v208 offset:57344
	ds_read_b128 v[24:27], v208 offset:57472
	s_waitcnt lgkmcnt(0)
	v_mfma_f32_32x32x16_bf16 v[0:15], v[16:19], v[100:103], v[0:15]
	ds_read_b128 v[16:19], v207 offset:57344
	ds_read_b128 v[28:31], v207 offset:57472
	s_waitcnt lgkmcnt(0)
	v_mfma_f32_32x32x16_bf16 v[0:15], v[16:19], v[104:107], v[0:15]
	ds_read_b128 v[16:19], v206 offset:57344
	ds_read_b128 v[32:35], v206 offset:57472
	s_waitcnt lgkmcnt(0)
	v_mfma_f32_32x32x16_bf16 v[0:15], v[16:19], v[108:111], v[0:15]
	v_mfma_f32_32x32x16_bf16 v[0:15], v[20:23], v[112:115], v[0:15]
	v_mfma_f32_32x32x16_bf16 v[0:15], v[24:27], v[116:119], v[0:15]
	v_mfma_f32_32x32x16_bf16 v[0:15], v[28:31], v[120:123], v[0:15]
	v_mfma_f32_32x32x16_bf16 v[0:15], v[32:35], v[124:127], v[0:15]
	s_nop 11
	v_max3_f32 v0, v8, s4, v9
	v_max3_f32 v0, v0, v10, v11
	v_max3_f32 v0, v0, v12, v13
	v_max3_f32 v0, v0, v14, v15
	v_mov_b32_e32 v1, v0
	s_nop 1
	v_permlane32_swap_b32_e32 v0, v1
	v_max_f32_e32 v1, v1, v1
	v_max_f32_e32 v0, v0, v0
	v_max_f32_e32 v0, v0, v1
	v_add_f32_e32 v1, 0x7149f2ca, v0
	v_cmp_ge_f32_e32 vcc, s33, v1
	s_cmp_eq_u64 vcc, exec
	v_max_f32_e32 v2, 0xf149f2ca, v0
	s_cselect_b64 vcc, -1, 0
	v_cndmask_b32_e32 v144, v2, v189, vcc
	v_mov_b32_e32 v0, v9
	v_mov_b32_e32 v1, v10
	v_pk_add_f32 v[66:67], v[0:1], v[144:145] op_sel_hi:[1,0] neg_lo:[0,1] neg_hi:[0,1]
	v_mov_b32_e32 v0, v11
	v_mov_b32_e32 v1, v12
	v_pk_add_f32 v[68:69], v[0:1], v[144:145] op_sel_hi:[1,0] neg_lo:[0,1] neg_hi:[0,1]
	v_sub_f32_e32 v1, 0xf149f2ca, v2
	v_mov_b32_e32 v131, v8
	v_mov_b32_e32 v0, v13
	v_exp_f32_e32 v2, v1
	v_mov_b32_e32 v1, v14
	s_add_i32 s2, s2, s71
	v_pk_add_f32 v[64:65], v[130:131], v[144:145] op_sel_hi:[1,0] neg_lo:[0,1] neg_hi:[0,1]
	v_pk_add_f32 v[70:71], v[0:1], v[144:145] op_sel_hi:[1,0] neg_lo:[0,1] neg_hi:[0,1]
	v_or_b32_e32 v0, s2, v199
	v_exp_f32_e32 v178, v64
	v_sub_u32_e32 v173, v0, v201
	v_add_u32_e32 v0, v36, v200
	v_add_lshl_u32 v0, v0, s5, 8
	s_waitcnt vmcnt(4) lgkmcnt(0)
	s_barrier
	v_or_b32_e32 v1, v0, v211
	v_mov_b32_e32 v48, v129
	v_mov_b32_e32 v49, v129
	v_sub_f32_e32 v155, v15, v144
	v_cndmask_b32_e64 v174, v2, 1.0, vcc
	v_add_u32_e32 v140, v1, v210
	v_or3_b32 v142, v0, v212, v210
	v_mov_b32_e32 v50, v129
	v_mov_b32_e32 v51, v129
	v_mov_b32_e32 v52, v129
	v_mov_b32_e32 v53, v129
	v_mov_b32_e32 v54, v129
	v_mov_b32_e32 v55, v129
	v_mov_b32_e32 v56, v129
	v_mov_b32_e32 v57, v129
	v_mov_b32_e32 v58, v129
	v_mov_b32_e32 v59, v129
	v_mov_b32_e32 v60, v129
	v_mov_b32_e32 v61, v129
	v_mov_b32_e32 v62, v129
	v_mov_b32_e32 v63, v129
	v_mov_b64_e32 v[32:33], v[48:49]
	v_mov_b64_e32 v[16:17], v[48:49]
	v_mov_b64_e32 v[0:1], v[48:49]
	v_add_u32_e32 v171, s3, v133
	v_lshl_add_u32 v131, v201, 2, s3
	v_mov_b32_e32 v141, v129
	v_mov_b32_e32 v143, v129
	s_mov_b32 s2, 0
	v_mov_b32_e32 v172, 0
	s_mov_b32 s90, 0x8000
	s_movk_i32 s91, 0xbf
	v_mov_b64_e32 v[34:35], v[50:51]
	v_mov_b64_e32 v[36:37], v[52:53]
	v_mov_b64_e32 v[38:39], v[54:55]
	v_mov_b64_e32 v[40:41], v[56:57]
	v_mov_b64_e32 v[42:43], v[58:59]
	v_mov_b64_e32 v[44:45], v[60:61]
	v_mov_b64_e32 v[46:47], v[62:63]
	v_mov_b64_e32 v[18:19], v[50:51]
	v_mov_b64_e32 v[20:21], v[52:53]
	v_mov_b64_e32 v[22:23], v[54:55]
	v_mov_b64_e32 v[24:25], v[56:57]
	v_mov_b64_e32 v[26:27], v[58:59]
	v_mov_b64_e32 v[28:29], v[60:61]
	v_mov_b64_e32 v[30:31], v[62:63]
	v_mov_b64_e32 v[2:3], v[50:51]
	v_mov_b64_e32 v[4:5], v[52:53]
	v_mov_b64_e32 v[6:7], v[54:55]
	v_mov_b64_e32 v[8:9], v[56:57]
	v_mov_b64_e32 v[10:11], v[58:59]
	v_mov_b64_e32 v[12:13], v[60:61]
	v_mov_b64_e32 v[14:15], v[62:63]
	s_mov_b32 s72, 0
	v_mov_b32_e32 v211, v178
	v_mov_b32_e32 v208, v178
	v_mov_b32_e32 v210, v178
	v_mov_b32_e32 v206, v178
	v_mov_b32_e32 v209, v178
	v_mov_b32_e32 v205, v178
	v_mov_b32_e32 v207, v178
	v_mov_b32_e32 v202, v178
	v_mov_b32_e32 v204, v178
	v_mov_b32_e32 v200, v178
	v_mov_b32_e32 v203, v178
	v_mov_b32_e32 v198, v178
	v_mov_b32_e32 v201, v178
	v_mov_b32_e32 v179, v178
	v_mov_b32_e32 v199, v178
	v_mov_b32_e32 v158, v64
	v_mov_b32_e32 v159, v64
	v_mov_b32_e32 v162, v64
	v_mov_b32_e32 v163, v64
	v_mov_b32_e32 v166, v64
	v_mov_b32_e32 v167, v64
	v_mov_b32_e32 v156, v64
	v_mov_b32_e32 v157, v64
	v_mov_b32_e32 v160, v65
	v_mov_b32_e32 v161, v66
	v_mov_b32_e32 v164, v67
	v_mov_b32_e32 v165, v68
	v_mov_b32_e32 v168, v69
	v_mov_b32_e32 v169, v70
	v_mov_b32_e32 v154, v71
	v_readlane_b32 s96, v247, 9
	v_readlane_b32 s97, v247, 8

; __global__ void __launch_bounds__(NTHREADS, 2) fox_fwd(Args args) {
;     extern __shared__ __attribute__((aligned(16))) unsigned char lds[];
	.amdhsa_kernel _Z7fox_fwd4Args
		.amdhsa_group_segment_fixed_size 0
		.amdhsa_private_segment_fixed_size 0
		.amdhsa_kernarg_size 360
		.amdhsa_user_sgpr_count 2
		.amdhsa_user_sgpr_dispatch_ptr 0
		.amdhsa_user_sgpr_queue_ptr 0
		.amdhsa_user_sgpr_kernarg_segment_ptr 1
		.amdhsa_user_sgpr_dispatch_id 0
		.amdhsa_user_sgpr_kernarg_preload_length 0
		.amdhsa_user_sgpr_kernarg_preload_offset 0
		.amdhsa_user_sgpr_private_segment_size 0
		.amdhsa_uses_dynamic_stack 0
		.amdhsa_enable_private_segment 0
		.amdhsa_system_sgpr_workgroup_id_x 1
		.amdhsa_system_sgpr_workgroup_id_y 0
		.amdhsa_system_sgpr_workgroup_id_z 0
		.amdhsa_system_sgpr_workgroup_info 0
		.amdhsa_system_vgpr_workitem_id 2
		.amdhsa_next_free_vgpr 254
		.amdhsa_next_free_sgpr 98
		.amdhsa_accum_offset 256
		.amdhsa_reserve_vcc 1
		.amdhsa_float_round_mode_32 0
		.amdhsa_float_round_mode_16_64 0
		.amdhsa_float_denorm_mode_32 3
		.amdhsa_float_denorm_mode_16_64 3
		.amdhsa_dx10_clamp 1
		.amdhsa_ieee_mode 1
		.amdhsa_fp16_overflow 0
		.amdhsa_tg_split 0
		.amdhsa_exception_fp_ieee_invalid_op 0
		.amdhsa_exception_fp_denorm_src 0
		.amdhsa_exception_fp_ieee_div_zero 0
		.amdhsa_exception_fp_ieee_overflow 0
		.amdhsa_exception_fp_ieee_underflow 0
		.amdhsa_exception_fp_ieee_inexact 0
		.amdhsa_exception_int_div_zero 0
	.end_amdhsa_kernel

; __global__ void __launch_bounds__(NTHREADS, 2) fox_fwd(Args args) {
;     extern __shared__ __attribute__((aligned(16))) unsigned char lds[];
amdhsa.kernels:
  - .agpr_count:     0
    .args:
      - .offset:         0
        .size:           104
        .value_kind:     by_value
      - .offset:         104
        .size:           4
        .value_kind:     hidden_block_count_x
      - .offset:         108
        .size:           4
        .value_kind:     hidden_block_count_y
      - .offset:         112
        .size:           4
        .value_kind:     hidden_block_count_z
      - .offset:         116
        .size:           2
        .value_kind:     hidden_group_size_x
      - .offset:         118
        .size:           2
        .value_kind:     hidden_group_size_y
      - .offset:         120
        .size:           2
        .value_kind:     hidden_group_size_z
      - .offset:         122
        .size:           2
        .value_kind:     hidden_remainder_x
      - .offset:         124
        .size:           2
        .value_kind:     hidden_remainder_y
      - .offset:         126
        .size:           2
        .value_kind:     hidden_remainder_z
      - .offset:         144
        .size:           8
        .value_kind:     hidden_global_offset_x
      - .offset:         152
        .size:           8
        .value_kind:     hidden_global_offset_y
      - .offset:         160
        .size:           8
        .value_kind:     hidden_global_offset_z
      - .offset:         168
        .size:           2
        .value_kind:     hidden_grid_dims
      - .offset:         192
        .size:           8
        .value_kind:     hidden_multigrid_sync_arg
      - .offset:         224
        .size:           4
        .value_kind:     hidden_dynamic_lds_size
    .group_segment_fixed_size: 0
    .kernarg_segment_align: 8
    .kernarg_segment_size: 360
    .language:       OpenCL C
    .language_version:
      - 2
      - 0
    .max_flat_workgroup_size: 512
    .name:           _Z7fox_fwd4Args
    .private_segment_fixed_size: 0
    .sgpr_count:     104
    .sgpr_spill_count: 95
    .symbol:         _Z7fox_fwd4Args.kd
    .uniform_work_group_size: 1
    .uses_dynamic_stack: false
    .vgpr_count:     254
    .vgpr_spill_count: 0
    .wavefront_size: 64
